# RG-LRU: log2(e) folded into the per-channel decay constant for exp(logu*r); GeLU argument constants folded (one multiply fewer each), f32
# speedup vs baseline: 1.0141x; 1.0068x over previous
; #define LAS __attribute__((address_space(3)))
; __device__ __forceinline__ float fsig(float x) { return __builtin_amdgcn_rcpf(1.0f + __expf(-x)); }
; template <bool PASS2>
; __device__ __forceinline__ void lru_item(const Frame& F, const Args& a, int item) {
;     ...
;                 for (int ks = 0; ks < 4; ++ks) { const bf16x8 xf = *(const LAS bf16x8*)(AT + (64 * s + 16 * rt + fr) * AT_PITCH + 64 * ks + 16 * fq);
;                     ar[rt] = __builtin_amdgcn_mfma_f32_16x16x32_bf16(xf, wrf[ks], ar[rt], 0, 0, 0); ai[rt] = __builtin_amdgcn_mfma_f32_16x16x32_bf16(xf, wif[ks], ai[rt], 0, 0, 0);
;                     if (ks == ks0) ax[rt] = __builtin_amdgcn_mfma_f32_16x16x32_bf16(xf, sel, ax[rt], 0, 0, 0); } }
;             const int tl0 = 64 * s + 16 * fq;
;             float A16 = 1.f, B16 = 0.f;
; #pragma unroll
;             for (int e = 0; e < 16; ++e) { const int ee = dir ? 15 - e : e; const int rt = ee >> 2, j = ee & 3;
;                 const float rg = fsig(ar[rt][j] + ba), ig = fsig(ai[rt][j] + bi); const float la = logu * rg; const float av = __expf(la);
.LBB0_150:
	v_mul_f32_e32 v191, 0x3fb8aa3b, v131
	s_mov_b32 s100, 0xbfb8aa3b
	v_mul_f32_e32 v181, 0xbfb8aa3b, v128
	v_mul_f32_e32 v190, 0xbfb8aa3b, v130
	v_add_u32_e32 v107, v132, v93
	v_add_u32_e32 v193, 0x11400, v107
	ds_read_b128 v[194:197], v193
	ds_read_b128 v[198:201], v193 offset:64
	ds_read_b128 v[202:205], v193 offset:128
	ds_read_b128 v[206:209], v193 offset:192
	ds_read_b128 v[210:213], v193 offset:4352
	ds_read_b128 v[214:217], v193 offset:4416
	ds_read_b128 v[218:221], v193 offset:4480
	ds_read_b128 v[222:225], v193 offset:4544
	ds_read_b128 v[226:229], v193 offset:8704
	ds_read_b128 v[248:251], v193 offset:8768
	ds_read_b128 v[252:255], v193 offset:8832
	v_cndmask_b32_e64 v40, 0, 1, s[2:3]
	v_cmp_ne_u32_e64 s[10:11], 1, v40
	s_mov_b32 s14, s12
	s_mov_b32 s15, s12
	s_mov_b32 s13, s12
	v_mov_b64_e32 v[66:67], s[14:15]
	v_mov_b64_e32 v[64:65], s[12:13]
	s_andn2_b64 vcc, exec, s[2:3]
	s_waitcnt vmcnt(9) lgkmcnt(10)
	v_mfma_f32_16x16x32_bf16 v[44:47], v[194:197], v[4:7], 0
	s_waitcnt vmcnt(3)
	v_mfma_f32_16x16x32_bf16 v[40:43], v[194:197], v[20:23], 0
	s_cbranch_vccnz .LBB0_152
	v_mfma_f32_16x16x32_bf16 v[64:67], v[194:197], v[0:3], 0

; __device__ __forceinline__ float fsig(float x) { return __builtin_amdgcn_rcpf(1.0f + __expf(-x)); }
; template <bool PASS2>
; __device__ __forceinline__ void lru_item(const Frame& F, const Args& a, int item) {
;     ...
;             for (int e = 0; e < 16; ++e) { const int ee = dir ? 15 - e : e; const int rt = ee >> 2, j = ee & 3;
;                 const float rg = fsig(ar[rt][j] + ba), ig = fsig(ai[rt][j] + bi); const float la = logu * rg; const float av = __expf(la);
;                 const float mult = (t0 + tl0 + ee == tstart) ? 1.0f : __builtin_amdgcn_sqrtf(fmaxf(1.0f - av * av, 0.f)); const float bv = mult * ig * ax[rt][j];
;                 ar[rt][j] = av; ai[rt][j] = bv; B16 = av * B16 + bv; A16 = av * A16; }
.LBB0_182:
	v_fma_f32 v80, v80, s100, v181
	v_exp_f32_e32 v80, v80
	v_fma_f32 v76, v76, s100, v190
	v_add_f32_e32 v80, 1.0, v80
	v_rcp_f32_e32 v80, v80
	v_fma_f32 v81, v81, s100, v181
	v_exp_f32_e32 v76, v76
	v_exp_f32_e32 v81, v81
	v_mul_f32_e32 v80, v191, v80
	v_exp_f32_e32 v80, v80
	v_add_f32_e32 v76, 1.0, v76
	v_add_f32_e32 v81, 1.0, v81
	v_rcp_f32_e32 v76, v76
	v_fma_f32 v85, -v80, v80, 1.0
	v_max_f32_e32 v85, 0, v85
	v_sqrt_f32_e32 v85, v85
	v_add_u32_e32 v84, s39, v127
	v_rcp_f32_e32 v81, v81
	v_cmp_ne_u32_e32 vcc, 0, v84
	v_fma_f32 v82, v82, s100, v181
	v_cndmask_b32_e32 v84, 1.0, v85, vcc
	v_mul_f32_e32 v76, v76, v84
	v_mul_f32_e32 v64, v76, v64
	v_add_f32_e32 v76, v130, v77
	v_mul_f32_e32 v77, v191, v81
	v_mul_f32_e32 v76, 0xbfb8aa3b, v76
	v_exp_f32_e32 v77, v77
	v_exp_f32_e32 v76, v76
	v_exp_f32_e32 v82, v82
	v_fmac_f32_e32 v64, 0, v80
	v_fma_f32 v81, -v77, v77, 1.0
	v_add_f32_e32 v76, 1.0, v76
	v_max_f32_e32 v81, 0, v81
	v_rcp_f32_e32 v76, v76
	v_sqrt_f32_e32 v81, v81
	v_mul_f32_e32 v64, v77, v64
	v_mul_f32_e32 v77, v80, v77
	v_mul_f32_e32 v76, v76, v81
	v_fmac_f32_e32 v64, v76, v65
	v_add_f32_e32 v65, 1.0, v82
	v_rcp_f32_e32 v65, v65
	v_fma_f32 v76, v78, s100, v190
	v_exp_f32_e32 v76, v76
	v_mul_f32_e32 v65, v191, v65
	v_exp_f32_e32 v65, v65
	v_add_f32_e32 v76, 1.0, v76
	v_rcp_f32_e32 v76, v76
	v_fma_f32 v80, v83, s100, v181
	v_fma_f32 v78, -v65, v65, 1.0
	v_max_f32_e32 v78, 0, v78
	v_sqrt_f32_e32 v78, v78
	v_exp_f32_e32 v80, v80
	v_mul_f32_e32 v64, v65, v64
	v_mul_f32_e32 v65, v65, v77
	v_mul_f32_e32 v76, v76, v78
	v_fmac_f32_e32 v64, v76, v66
	v_add_f32_e32 v66, 1.0, v80
	v_rcp_f32_e32 v66, v66
	v_fma_f32 v76, v79, s100, v190
	v_exp_f32_e32 v76, v76
	v_mul_f32_e32 v66, v191, v66
	v_exp_f32_e32 v66, v66
	v_add_f32_e32 v76, 1.0, v76
	v_rcp_f32_e32 v76, v76
	v_fma_f32 v77, -v66, v66, 1.0
	v_max_f32_e32 v77, 0, v77
	v_sqrt_f32_e32 v77, v77
	v_fma_f32 v72, v72, s100, v181
	v_exp_f32_e32 v72, v72
	v_mul_f32_e32 v64, v66, v64
	v_mul_f32_e32 v76, v76, v77
	v_fmac_f32_e32 v64, v76, v67
	v_add_f32_e32 v67, 1.0, v72
	v_rcp_f32_e32 v67, v67
	v_fma_f32 v68, v68, s100, v190
	v_exp_f32_e32 v68, v68
	v_mul_f32_e32 v67, v191, v67
	v_exp_f32_e32 v67, v67
	v_mul_f32_e32 v65, v66, v65
	v_add_f32_e32 v66, 1.0, v68
	v_rcp_f32_e32 v66, v66
	v_fma_f32 v68, -v67, v67, 1.0
	v_max_f32_e32 v68, 0, v68
	v_sqrt_f32_e32 v68, v68
	v_fma_f32 v72, v73, s100, v181
	v_exp_f32_e32 v72, v72
	v_mul_f32_e32 v66, v66, v68
	v_mul_f32_e32 v52, v66, v52
	v_fmac_f32_e32 v52, v64, v67
	v_add_f32_e32 v64, 1.0, v72
	v_rcp_f32_e32 v64, v64
	v_fma_f32 v66, v69, s100, v190
	v_exp_f32_e32 v66, v66
	v_mul_f32_e32 v64, v191, v64
	v_exp_f32_e32 v64, v64
	v_mul_f32_e32 v65, v65, v67
	v_add_f32_e32 v66, 1.0, v66
	v_fma_f32 v67, -v64, v64, 1.0
	v_max_f32_e32 v67, 0, v67
	v_rcp_f32_e32 v66, v66
	v_sqrt_f32_e32 v67, v67
	v_fma_f32 v68, v74, s100, v181
	v_exp_f32_e32 v68, v68
	v_mul_f32_e32 v52, v64, v52
	v_mul_f32_e32 v66, v66, v67
	v_fmac_f32_e32 v52, v66, v53
	v_add_f32_e32 v53, 1.0, v68
	v_rcp_f32_e32 v53, v53
	v_fma_f32 v66, v70, s100, v190
	v_exp_f32_e32 v66, v66
	v_mul_f32_e32 v53, v191, v53
	v_exp_f32_e32 v53, v53
	v_mul_f32_e32 v64, v64, v65
	v_add_f32_e32 v65, 1.0, v66
	v_fma_f32 v66, -v53, v53, 1.0
	v_max_f32_e32 v66, 0, v66
	v_rcp_f32_e32 v65, v65
	v_sqrt_f32_e32 v66, v66
	v_fma_f32 v67, v75, s100, v181
	v_exp_f32_e32 v67, v67
	v_mul_f32_e32 v52, v53, v52
	v_mul_f32_e32 v65, v65, v66
	v_fmac_f32_e32 v52, v65, v54
	v_add_f32_e32 v54, 1.0, v67
	v_rcp_f32_e32 v54, v54
	v_fma_f32 v65, v71, s100, v190
	v_exp_f32_e32 v65, v65
	v_mul_f32_e32 v54, v191, v54
	v_exp_f32_e32 v54, v54
	v_mul_f32_e32 v53, v53, v64
	v_add_f32_e32 v64, 1.0, v65
	v_fma_f32 v65, -v54, v54, 1.0
	v_max_f32_e32 v65, 0, v65
	v_rcp_f32_e32 v64, v64
	v_sqrt_f32_e32 v65, v65
	v_fma_f32 v60, v60, s100, v181
	v_exp_f32_e32 v60, v60
	v_mul_f32_e32 v52, v54, v52
	v_mul_f32_e32 v64, v64, v65
	v_fmac_f32_e32 v52, v64, v55
	v_add_f32_e32 v55, 1.0, v60
	v_rcp_f32_e32 v55, v55
	v_fma_f32 v56, v56, s100, v190
	v_exp_f32_e32 v56, v56
	v_mul_f32_e32 v55, v191, v55
	v_exp_f32_e32 v55, v55
	v_mul_f32_e32 v53, v54, v53
	v_add_f32_e32 v54, 1.0, v56
	v_rcp_f32_e32 v54, v54
	v_fma_f32 v56, -v55, v55, 1.0
	v_max_f32_e32 v56, 0, v56
	v_sqrt_f32_e32 v56, v56
	v_fma_f32 v60, v61, s100, v181
	v_exp_f32_e32 v60, v60
	v_mul_f32_e32 v54, v54, v56
	v_mul_f32_e32 v40, v54, v40
	v_fmac_f32_e32 v40, v52, v55
	v_add_f32_e32 v52, 1.0, v60
; #define LAS __attribute__((address_space(3)))
; __device__ __forceinline__ unsigned cvt_pk_bf16(float lo, float hi) { unsigned r; asm volatile("v_cvt_pk_bf16_f32 %0, %1, %2" : "=v"(r) : "v"(lo), "v"(hi)); return r; }
; __device__ __forceinline__ float bf2f(unsigned short b) { return __uint_as_float(((unsigned)b) << 16); }
; __device__ __forceinline__ float fsig(float x) { return __builtin_amdgcn_rcpf(1.0f + __expf(-x)); }
; template <bool PASS2>
; __device__ __forceinline__ void lru_item(const Frame& F, const Args& a, int item) {
;     ...
;             for (int e = 0; e < 16; ++e) { const int ee = dir ? 15 - e : e; const int rt = ee >> 2, j = ee & 3;
;                 const float rg = fsig(ar[rt][j] + ba), ig = fsig(ai[rt][j] + bi); const float la = logu * rg; const float av = __expf(la);
;                 const float mult = (t0 + tl0 + ee == tstart) ? 1.0f : __builtin_amdgcn_sqrtf(fmaxf(1.0f - av * av, 0.f)); const float bv = mult * ig * ax[rt][j];
;                 ar[rt][j] = av; ai[rt][j] = bv; B16 = av * B16 + bv; A16 = av * A16; }
;             const int pos = dir ? 3 - fq : fq;
;             float PA = 1.f, PB = 0.f, QA = 1.f, QB = 0.f;
; #pragma unroll
;             for (int i = 0; i < 4; ++i) { const int k = dir ? 3 - i : i; const float Ak = __shfl(A16, fr + 16 * k), Bk = __shfl(B16, fr + 16 * k);
;                 if (i < pos) { PB = Ak * PB + Bk; PA = Ak * PA; }
;                 QB = Ak * QB + Bk; QA = Ak * QA; }
;             if (PASS2) {
;                 float h = PA * hc + PB;
; #pragma unroll
;                 for (int e = 0; e < 16; ++e) { const int ee = dir ? 15 - e : e; const int rt = ee >> 2, j = ee & 3; h = ar[rt][j] * h + ai[rt][j];
;                     if (dir == 0) hf[3][rt][j] = h;
;                     else { LAS unsigned short* yp = (LAS unsigned short*)(R0 + (tl0 + ee) * AT_PITCH + 2 * c); const float yb = bf2f(*yp);
;                         const float u2 = 1.5957691216057308f * (yb + 0.044715f * yb * yb * yb);
;                         const float y = (hf[3][rt][j] + h) * yb * fsig(u2);
;                         *yp = (unsigned short)(cvt_pk_bf16(y, 0.f) & 0xffffu); } }
;                 hc = QA * hc + QB;
;             } else { TB = QA * TB + QB; TA = QA * TA; }
	v_rcp_f32_e32 v52, v52
	v_fma_f32 v54, v57, s100, v190
	v_exp_f32_e32 v54, v54
	v_mul_f32_e32 v52, v191, v52
	v_exp_f32_e32 v52, v52
	v_mul_f32_e32 v53, v53, v55
	v_add_f32_e32 v54, 1.0, v54
	v_fma_f32 v55, -v52, v52, 1.0
	v_max_f32_e32 v55, 0, v55
	v_rcp_f32_e32 v54, v54
	v_sqrt_f32_e32 v55, v55
	v_fma_f32 v56, v62, s100, v181
	v_exp_f32_e32 v56, v56
	v_mul_f32_e32 v40, v52, v40
	v_mul_f32_e32 v54, v54, v55
	v_fmac_f32_e32 v40, v54, v41
	v_add_f32_e32 v41, 1.0, v56
	v_rcp_f32_e32 v41, v41
	v_fma_f32 v54, v58, s100, v190
	v_exp_f32_e32 v54, v54
	v_mul_f32_e32 v41, v191, v41
	v_exp_f32_e32 v41, v41
	v_mul_f32_e32 v52, v52, v53
	v_add_f32_e32 v53, 1.0, v54
	v_fma_f32 v54, -v41, v41, 1.0
	v_max_f32_e32 v54, 0, v54
	v_rcp_f32_e32 v53, v53
	v_sqrt_f32_e32 v54, v54
	v_fma_f32 v55, v63, s100, v181
	v_exp_f32_e32 v55, v55
	v_mul_f32_e32 v40, v41, v40
	v_mul_f32_e32 v53, v53, v54
	v_fmac_f32_e32 v40, v53, v42
	v_add_f32_e32 v42, 1.0, v55
	v_rcp_f32_e32 v42, v42
	v_fma_f32 v53, v59, s100, v190
	v_exp_f32_e32 v53, v53
	v_mul_f32_e32 v42, v191, v42
	v_exp_f32_e32 v54, v42
	v_mul_f32_e32 v41, v41, v52
	v_add_f32_e32 v42, 1.0, v53
	v_fma_f32 v52, -v54, v54, 1.0
	v_max_f32_e32 v52, 0, v52
	v_rcp_f32_e32 v42, v42
	v_sqrt_f32_e32 v52, v52
	v_fma_f32 v48, v48, s100, v181
	v_exp_f32_e32 v48, v48
	v_mul_f32_e32 v40, v54, v40
	v_mul_f32_e32 v42, v42, v52
	v_fmac_f32_e32 v40, v42, v43
	v_add_f32_e32 v42, 1.0, v48
	v_rcp_f32_e32 v42, v42
	v_fma_f32 v48, v49, s100, v181
	v_mul_f32_e32 v42, v191, v42
	v_fma_f32 v43, v44, s100, v190
	v_exp_f32_e32 v52, v48
	v_exp_f32_e32 v43, v43
	v_exp_f32_e32 v42, v42
	v_pk_mov_b32 v[48:49], v[36:37], v[36:37] op_sel:[1,0]
	v_add_f32_e32 v36, 1.0, v52
	v_mul_f32_e32 v44, v54, v41
	v_add_f32_e32 v41, 1.0, v43
	v_fma_f32 v43, -v42, v42, 1.0
	v_rcp_f32_e32 v36, v36
	v_max_f32_e32 v43, 0, v43
	v_rcp_f32_e32 v41, v41
	v_sqrt_f32_e32 v43, v43
	v_fma_f32 v50, v50, s100, v181
	v_exp_f32_e32 v50, v50
	v_mul_f32_e32 v36, v191, v36
	v_mul_f32_e32 v41, v41, v43
	v_mov_b32_e32 v43, v49
	v_fma_f32 v45, v45, s100, v190
	v_exp_f32_e32 v49, v36
	v_mul_f32_e32 v36, v40, v42
	v_exp_f32_e32 v45, v45
	v_pk_fma_f32 v[40:41], v[40:41], v[42:43], v[36:37] op_sel_hi:[1,1,0]
	v_add_f32_e32 v36, 1.0, v50
	v_rcp_f32_e32 v36, v36
	v_fma_f32 v52, -v49, v49, 1.0
	v_add_f32_e32 v45, 1.0, v45
	v_max_f32_e32 v52, 0, v52
	v_rcp_f32_e32 v45, v45
	v_sqrt_f32_e32 v52, v52
	v_fma_f32 v43, v46, s100, v190
	v_mul_f32_e32 v36, v191, v36
	v_mul_f32_e32 v42, v44, v42
	v_exp_f32_e32 v44, v43
	v_exp_f32_e32 v43, v36
	v_mul_f32_e32 v40, v45, v52
	v_mul_f32_e32 v36, v40, v37
	v_add_f32_e32 v37, 1.0, v44
	v_rcp_f32_e32 v44, v37
	v_fma_f32 v37, -v43, v43, 1.0
	v_max_f32_e32 v37, 0, v37
	v_sqrt_f32_e32 v45, v37
	v_fma_f32 v37, v51, s100, v181
	v_exp_f32_e32 v46, v37
	v_pk_fma_f32 v[36:37], v[40:41], v[48:49], v[36:37] op_sel_hi:[1,1,0]
	v_mul_f32_e32 v40, v49, v42
	v_add_f32_e32 v41, 1.0, v46
	v_rcp_f32_e32 v41, v41
	v_fma_f32 v42, v47, s100, v190
	v_mul_f32_e32 v36, v44, v45
	v_exp_f32_e32 v44, v42
	v_mul_f32_e32 v41, v191, v41
	v_exp_f32_e32 v41, v41
	v_add_f32_e32 v44, 1.0, v44
	v_rcp_f32_e32 v44, v44
	v_mov_b32_e32 v42, v38
	v_fma_f32 v45, -v41, v41, 1.0
	v_max_f32_e32 v45, 0, v45
	v_sqrt_f32_e32 v45, v45
	v_mul_f32_e32 v38, v36, v38
	v_pk_fma_f32 v[36:37], v[36:37], v[42:43], v[38:39] op_sel_hi:[1,1,0]
	v_mul_f32_e32 v42, v43, v40
	v_mul_f32_e32 v36, v44, v45
	v_mov_b32_e32 v40, v39
	v_mul_f32_e32 v38, v37, v41
	v_pk_fma_f32 v[36:37], v[36:37], v[40:41], v[38:39] op_sel_hi:[1,1,0]
	ds_bpermute_b32 v43, v124, v36
	v_mul_f32_e32 v37, v41, v42
	ds_bpermute_b32 v40, v122, v37
	ds_bpermute_b32 v41, v122, v36
	ds_bpermute_b32 v42, v124, v37
	ds_bpermute_b32 v38, v125, v37
	ds_bpermute_b32 v44, v125, v36
	ds_bpermute_b32 v39, v126, v37
	s_waitcnt lgkmcnt(4)
	v_fmac_f32_e32 v41, 0, v40
	ds_bpermute_b32 v45, v126, v36
	s_waitcnt lgkmcnt(4)
	v_fmac_f32_e32 v43, v41, v42
	s_waitcnt lgkmcnt(3)
	v_mul_f32_e32 v37, v43, v38
	v_mul_f32_e32 v36, v40, v42
	s_waitcnt lgkmcnt(2)
	v_add_f32_e32 v37, v37, v44
	s_waitcnt lgkmcnt(1)
	v_pk_mul_f32 v[36:37], v[36:37], v[38:39]
	s_add_i32 s39, s39, 64
	v_mul_f32_e32 v36, v36, v39
	s_waitcnt lgkmcnt(0)
	v_add_f32_e32 v107, v37, v45
	v_fmac_f32_e32 v107, v129, v36
	v_mul_f32_e32 v106, v106, v36
	s_cmpk_eq_i32 s39, 0x100
	v_add_u32_e32 v132, 0x4400, v132
	s_cbranch_scc1 .LBB0_184
	v_mov_b32_e32 v129, v107
	s_branch .LBB0_150

; #define LAS __attribute__((address_space(3)))
; template <bool PASS2>
; __device__ __forceinline__ void lru_item(const Frame& F, const Args& a, int item) {
;     ...
;         for (int si = 0; si < 4; ++si) { const int s = dir ? 3 - si : si;
;             if (PASS2 && dir == 0) {
; #pragma unroll
;                 for (int i1 = 0; i1 < 4; ++i1)
; #pragma unroll
;                     for (int i2 = 0; i2 < 4; ++i2) { hf[0][i1][i2] = hf[1][i1][i2]; hf[1][i1][i2] = hf[2][i1][i2]; hf[2][i1][i2] = hf[3][i1][i2]; } }
;             f32x4 ar[4], ai[4], ax[4];
; #pragma unroll
;             for (int rt = 0; rt < 4; ++rt) { ar[rt] = (f32x4){0.f, 0.f, 0.f, 0.f}; ai[rt] = (f32x4){0.f, 0.f, 0.f, 0.f}; ax[rt] = (f32x4){0.f, 0.f, 0.f, 0.f};
; #pragma unroll
;                 for (int ks = 0; ks < 4; ++ks) { const bf16x8 xf = *(const LAS bf16x8*)(AT + (64 * s + 16 * rt + fr) * AT_PITCH + 64 * ks + 16 * fq);
;                     ar[rt] = __builtin_amdgcn_mfma_f32_16x16x32_bf16(xf, wrf[ks], ar[rt], 0, 0, 0); ai[rt] = __builtin_amdgcn_mfma_f32_16x16x32_bf16(xf, wif[ks], ai[rt], 0, 0, 0);
;                     if (ks == ks0) ax[rt] = __builtin_amdgcn_mfma_f32_16x16x32_bf16(xf, sel, ax[rt], 0, 0, 0); } }
.LBB0_187:
	v_mul_f32_e32 v191, 0x3fb8aa3b, v130
	s_mov_b32 s100, 0xbfb8aa3b
	v_mul_f32_e32 v181, 0xbfb8aa3b, v128
	v_mul_f32_e32 v190, 0xbfb8aa3b, v129
	v_bitop3_b32 v36, s39, v101, v123 bitop3:0xde
	v_mul_lo_u32 v36, v36, s45
	v_add_u32_e32 v107, v110, v36
	ds_read_b128 v[194:197], v107
	ds_read_b128 v[198:201], v107 offset:64
	ds_read_b128 v[202:205], v107 offset:128
	ds_read_b128 v[206:209], v107 offset:192
	ds_read_b128 v[210:213], v107 offset:4352
	ds_read_b128 v[214:217], v107 offset:4416
	ds_read_b128 v[218:221], v107 offset:4480
	ds_read_b128 v[222:225], v107 offset:4544
	ds_read_b128 v[226:229], v107 offset:8704
	ds_read_b128 v[248:251], v107 offset:8768
	ds_read_b128 v[252:255], v107 offset:8832
	s_mov_b32 s14, s12
	s_mov_b32 s15, s12
	s_mov_b32 s13, s12
	v_mov_b64_e32 v[38:39], s[14:15]
	s_and_b64 vcc, exec, s[10:11]
	v_mov_b64_e32 v[36:37], s[12:13]
	s_waitcnt vmcnt(9) lgkmcnt(10)
	v_mfma_f32_16x16x32_bf16 v[44:47], v[194:197], v[4:7], 0
	s_waitcnt vmcnt(3)
	v_mfma_f32_16x16x32_bf16 v[48:51], v[194:197], v[20:23], 0
	s_cbranch_vccnz .LBB0_189
	v_mfma_f32_16x16x32_bf16 v[36:39], v[194:197], v[0:3], 0

; __device__ __forceinline__ float fsig(float x) { return __builtin_amdgcn_rcpf(1.0f + __expf(-x)); }
; template <bool PASS2>
; __device__ __forceinline__ void lru_item(const Frame& F, const Args& a, int item) {
;     ...
;             for (int e = 0; e < 16; ++e) { const int ee = dir ? 15 - e : e; const int rt = ee >> 2, j = ee & 3;
;                 const float rg = fsig(ar[rt][j] + ba), ig = fsig(ai[rt][j] + bi); const float la = logu * rg; const float av = __expf(la);
;                 const float mult = (t0 + tl0 + ee == tstart) ? 1.0f : __builtin_amdgcn_sqrtf(fmaxf(1.0f - av * av, 0.f)); const float bv = mult * ig * ax[rt][j];
;                 ar[rt][j] = av; ai[rt][j] = bv; B16 = av * B16 + bv; A16 = av * A16; }
.LBB0_219:
	s_nop 4
	v_fma_f32 v83, v83, s100, v181
	v_exp_f32_e32 v83, v83
	v_fma_f32 v82, v82, s100, v181
	v_exp_f32_e32 v82, v82
	v_add_f32_e32 v83, 1.0, v83
	v_rcp_f32_e32 v83, v83
	v_fma_f32 v79, v79, s100, v190
	v_add_f32_e32 v82, 1.0, v82
	v_mul_f32_e32 v83, v191, v83
	v_exp_f32_e32 v83, v83
	v_exp_f32_e32 v79, v79
	v_rcp_f32_e32 v82, v82
	s_xor_b32 s13, s39, 0xc0
	v_fma_f32 v85, -v83, v83, 1.0
	v_max_f32_e32 v85, 0, v85
	v_add_f32_e32 v79, 1.0, v79
	v_sqrt_f32_e32 v85, v85
	v_mul_f32_e32 v82, v191, v82
	v_rcp_f32_e32 v79, v79
	v_add_u32_e32 v84, s13, v127
	v_fma_f32 v78, v78, s100, v190
	v_exp_f32_e32 v82, v82
	v_cmp_ne_u32_e32 vcc, s54, v84
	v_exp_f32_e32 v78, v78
	v_cndmask_b32_e32 v84, 1.0, v85, vcc
	v_mul_f32_e32 v79, v79, v84
	v_mul_f32_e32 v75, v79, v75
	v_fma_f32 v79, -v82, v82, 1.0
	v_add_f32_e32 v78, 1.0, v78
	v_max_f32_e32 v79, 0, v79
	v_fma_f32 v81, v81, s100, v181
	v_rcp_f32_e32 v78, v78
	v_sqrt_f32_e32 v79, v79
	v_exp_f32_e32 v81, v81
	v_fma_f32 v77, v77, s100, v190
	v_mul_f32_e32 v78, v78, v79
	v_add_f32_e32 v79, 1.0, v81
	v_rcp_f32_e32 v79, v79
	v_exp_f32_e32 v77, v77
	v_fmac_f32_e32 v75, 0, v83
	v_mul_f32_e32 v75, v82, v75
	v_mul_f32_e32 v79, v191, v79
	v_exp_f32_e32 v79, v79
	v_fmac_f32_e32 v75, v78, v74
	v_add_f32_e32 v74, 1.0, v77
	v_fma_f32 v77, -v79, v79, 1.0
	v_max_f32_e32 v77, 0, v77
	v_fma_f32 v78, v80, s100, v181
	v_rcp_f32_e32 v74, v74
	v_sqrt_f32_e32 v77, v77
	v_exp_f32_e32 v78, v78
	v_fma_f32 v71, v71, s100, v181
	v_mul_f32_e32 v74, v74, v77
	v_add_f32_e32 v77, 1.0, v78
	v_rcp_f32_e32 v77, v77
	v_exp_f32_e32 v71, v71
	v_fma_f32 v76, v76, s100, v190
	v_mul_f32_e32 v77, v191, v77
	v_exp_f32_e32 v77, v77
	v_add_f32_e32 v71, 1.0, v71
	v_exp_f32_e32 v76, v76
	v_rcp_f32_e32 v71, v71
	v_fma_f32 v70, v70, s100, v181
	v_mul_f32_e32 v75, v79, v75
	v_exp_f32_e32 v70, v70
	v_fmac_f32_e32 v75, v74, v73
	v_fma_f32 v74, -v77, v77, 1.0
	v_add_f32_e32 v73, 1.0, v76
	v_max_f32_e32 v74, 0, v74
	v_mul_f32_e32 v71, v191, v71
	v_rcp_f32_e32 v73, v73
	v_sqrt_f32_e32 v74, v74
	v_fma_f32 v67, v67, s100, v190
	v_exp_f32_e32 v71, v71
	v_add_f32_e32 v70, 1.0, v70
	v_exp_f32_e32 v67, v67
	v_rcp_f32_e32 v70, v70
	v_mul_f32_e32 v73, v73, v74
	v_mul_f32_e32 v74, v77, v75
	v_fmac_f32_e32 v74, v73, v72
	v_fma_f32 v72, -v71, v71, 1.0
	v_add_f32_e32 v67, 1.0, v67
	v_max_f32_e32 v72, 0, v72
	v_mul_f32_e32 v70, v191, v70
	v_rcp_f32_e32 v67, v67
	v_sqrt_f32_e32 v72, v72
	v_fma_f32 v66, v66, s100, v190
	v_exp_f32_e32 v66, v66
	v_exp_f32_e32 v70, v70
	v_mul_f32_e32 v67, v67, v72
	v_mul_f32_e32 v72, v71, v74
	v_fmac_f32_e32 v72, v67, v63
	v_add_f32_e32 v63, 1.0, v66
	v_fma_f32 v66, -v70, v70, 1.0
	v_max_f32_e32 v66, 0, v66
	v_fma_f32 v67, v69, s100, v181
	v_rcp_f32_e32 v63, v63
	v_sqrt_f32_e32 v66, v66
	v_exp_f32_e32 v67, v67
	v_fma_f32 v65, v65, s100, v190
	v_exp_f32_e32 v65, v65
	v_mul_f32_e32 v63, v63, v66
	v_mul_f32_e32 v66, v70, v72
	v_add_f32_e32 v67, 1.0, v67
	v_rcp_f32_e32 v67, v67
	v_fmac_f32_e32 v66, v63, v62
	v_add_f32_e32 v62, 1.0, v65
	v_fma_f32 v65, v68, s100, v181
	v_exp_f32_e32 v65, v65
	v_mul_f32_e32 v67, v191, v67
	v_exp_f32_e32 v67, v67
	v_add_f32_e32 v65, 1.0, v65
	v_rcp_f32_e32 v65, v65
	v_fma_f32 v59, v59, s100, v181
	v_exp_f32_e32 v59, v59
	v_fma_f32 v63, -v67, v67, 1.0
	v_max_f32_e32 v63, 0, v63
	v_mul_f32_e32 v65, v191, v65
	v_rcp_f32_e32 v62, v62
	v_sqrt_f32_e32 v63, v63
	v_fma_f32 v64, v64, s100, v190
	v_exp_f32_e32 v65, v65
	v_add_f32_e32 v59, 1.0, v59
	v_exp_f32_e32 v64, v64
	v_rcp_f32_e32 v59, v59
	v_fma_f32 v58, v58, s100, v181
	v_mul_f32_e32 v62, v62, v63
	v_mul_f32_e32 v63, v67, v66
	v_exp_f32_e32 v58, v58
	v_fmac_f32_e32 v63, v62, v61
	v_fma_f32 v62, -v65, v65, 1.0
	v_add_f32_e32 v61, 1.0, v64
	v_max_f32_e32 v62, 0, v62
	v_mul_f32_e32 v59, v191, v59
	v_rcp_f32_e32 v61, v61
	v_sqrt_f32_e32 v62, v62
	v_fma_f32 v55, v55, s100, v190
	v_exp_f32_e32 v59, v59
	v_add_f32_e32 v58, 1.0, v58
	v_exp_f32_e32 v55, v55
	v_rcp_f32_e32 v58, v58
	v_mul_f32_e32 v61, v61, v62
	v_mul_f32_e32 v62, v65, v63
	v_fmac_f32_e32 v62, v61, v60
	v_fma_f32 v60, -v59, v59, 1.0
	v_add_f32_e32 v55, 1.0, v55
	v_max_f32_e32 v60, 0, v60
	v_mul_f32_e32 v58, v191, v58
	v_rcp_f32_e32 v55, v55
	v_sqrt_f32_e32 v60, v60
	v_fma_f32 v54, v54, s100, v190
	v_exp_f32_e32 v54, v54
	v_exp_f32_e32 v58, v58
	v_mul_f32_e32 v55, v55, v60
	v_mul_f32_e32 v60, v59, v62
	v_fmac_f32_e32 v60, v55, v51
; #define LAS __attribute__((address_space(3)))
; __device__ __forceinline__ unsigned cvt_pk_bf16(float lo, float hi) { unsigned r; asm volatile("v_cvt_pk_bf16_f32 %0, %1, %2" : "=v"(r) : "v"(lo), "v"(hi)); return r; }
; __device__ __forceinline__ float bf2f(unsigned short b) { return __uint_as_float(((unsigned)b) << 16); }
; __device__ __forceinline__ float fsig(float x) { return __builtin_amdgcn_rcpf(1.0f + __expf(-x)); }
; template <bool PASS2>
; __device__ __forceinline__ void lru_item(const Frame& F, const Args& a, int item) {
;     ...
;             for (int e = 0; e < 16; ++e) { const int ee = dir ? 15 - e : e; const int rt = ee >> 2, j = ee & 3;
;                 const float rg = fsig(ar[rt][j] + ba), ig = fsig(ai[rt][j] + bi); const float la = logu * rg; const float av = __expf(la);
;                 const float mult = (t0 + tl0 + ee == tstart) ? 1.0f : __builtin_amdgcn_sqrtf(fmaxf(1.0f - av * av, 0.f)); const float bv = mult * ig * ax[rt][j];
;                 ar[rt][j] = av; ai[rt][j] = bv; B16 = av * B16 + bv; A16 = av * A16; }
;             const int pos = dir ? 3 - fq : fq;
;             float PA = 1.f, PB = 0.f, QA = 1.f, QB = 0.f;
; #pragma unroll
;             for (int i = 0; i < 4; ++i) { const int k = dir ? 3 - i : i; const float Ak = __shfl(A16, fr + 16 * k), Bk = __shfl(B16, fr + 16 * k);
;                 if (i < pos) { PB = Ak * PB + Bk; PA = Ak * PA; }
;                 QB = Ak * QB + Bk; QA = Ak * QA; }
;             if (PASS2) {
;                 float h = PA * hc + PB;
; #pragma unroll
;                 for (int e = 0; e < 16; ++e) { const int ee = dir ? 15 - e : e; const int rt = ee >> 2, j = ee & 3; h = ar[rt][j] * h + ai[rt][j];
;                     if (dir == 0) hf[3][rt][j] = h;
;                     else { LAS unsigned short* yp = (LAS unsigned short*)(R0 + (tl0 + ee) * AT_PITCH + 2 * c); const float yb = bf2f(*yp);
;                         const float u2 = 1.5957691216057308f * (yb + 0.044715f * yb * yb * yb);
;                         const float y = (hf[3][rt][j] + h) * yb * fsig(u2);
;                         *yp = (unsigned short)(cvt_pk_bf16(y, 0.f) & 0xffffu); } }
;                 hc = QA * hc + QB;
;             } else { TB = QA * TB + QB; TA = QA * TA; }
	v_add_f32_e32 v51, 1.0, v54
	v_fma_f32 v54, -v58, v58, 1.0
	v_max_f32_e32 v54, 0, v54
	v_fma_f32 v55, v57, s100, v181
	v_rcp_f32_e32 v51, v51
	v_sqrt_f32_e32 v54, v54
	v_exp_f32_e32 v55, v55
	v_fma_f32 v53, v53, s100, v190
	v_exp_f32_e32 v53, v53
	v_mul_f32_e32 v51, v51, v54
	v_mul_f32_e32 v54, v58, v60
	v_add_f32_e32 v55, 1.0, v55
	v_rcp_f32_e32 v55, v55
	v_fmac_f32_e32 v54, v51, v50
	v_add_f32_e32 v50, 1.0, v53
	v_fma_f32 v53, v56, s100, v181
	v_exp_f32_e32 v53, v53
	v_mul_f32_e32 v55, v191, v55
	v_exp_f32_e32 v55, v55
	v_add_f32_e32 v53, 1.0, v53
	v_rcp_f32_e32 v53, v53
	v_rcp_f32_e32 v50, v50
	v_fma_f32 v51, -v55, v55, 1.0
	v_max_f32_e32 v51, 0, v51
	v_mul_f32_e32 v53, v191, v53
	v_sqrt_f32_e32 v51, v51
	v_fma_f32 v52, v52, s100, v190
	v_exp_f32_e32 v53, v53
	v_exp_f32_e32 v52, v52
	v_mul_f32_e32 v50, v50, v51
	v_mul_f32_e32 v51, v55, v54
	v_fmac_f32_e32 v51, v50, v49
	v_fma_f32 v50, -v53, v53, 1.0
	v_add_f32_e32 v49, 1.0, v52
	v_max_f32_e32 v50, 0, v50
	v_fma_f32 v47, v47, s100, v181
	v_rcp_f32_e32 v49, v49
	v_sqrt_f32_e32 v50, v50
	v_exp_f32_e32 v52, v47
	v_fma_f32 v43, v43, s100, v190
	v_mul_f32_e32 v50, v49, v50
	v_add_f32_e32 v49, 1.0, v52
	v_rcp_f32_e32 v49, v49
	v_exp_f32_e32 v43, v43
	v_mul_f32_e32 v47, v53, v51
	v_fmac_f32_e32 v47, v50, v48
	v_mul_f32_e32 v49, v191, v49
	v_exp_f32_e32 v49, v49
	v_add_f32_e32 v43, 1.0, v43
	v_rcp_f32_e32 v43, v43
	v_fma_f32 v48, -v49, v49, 1.0
	v_max_f32_e32 v48, 0, v48
	v_sqrt_f32_e32 v48, v48
	v_fma_f32 v46, v46, s100, v181
	v_exp_f32_e32 v51, v46
	v_mul_f32_e32 v80, v83, v82
	v_mul_f32_e32 v46, v43, v48
	v_mov_b32_e32 v48, v39
	v_mul_f32_e32 v50, v46, v39
	v_add_f32_e32 v39, 1.0, v51
	v_rcp_f32_e32 v39, v39
	v_mul_f32_e32 v76, v79, v80
	v_mul_f32_e32 v73, v77, v76
	v_fma_f32 v42, v42, s100, v190
	v_mul_f32_e32 v39, v191, v39
	v_mul_f32_e32 v69, v71, v73
	v_exp_f32_e32 v42, v42
	v_mul_f32_e32 v68, v70, v69
	v_exp_f32_e32 v39, v39
	v_mul_f32_e32 v64, v67, v68
	v_mul_f32_e32 v61, v65, v64
	v_mul_f32_e32 v57, v59, v61
	v_add_f32_e32 v42, 1.0, v42
	v_mul_f32_e32 v56, v58, v57
	v_rcp_f32_e32 v52, v42
	v_fma_f32 v42, -v39, v39, 1.0
	v_mul_f32_e32 v54, v55, v56
	v_max_f32_e32 v42, 0, v42
	v_mul_f32_e32 v51, v53, v54
	v_sqrt_f32_e32 v53, v42
	v_fma_f32 v42, v45, s100, v181
	v_exp_f32_e32 v45, v42
	v_fma_f32 v41, v41, s100, v190
	v_exp_f32_e32 v41, v41
	v_add_f32_e32 v45, 1.0, v45
	v_rcp_f32_e32 v45, v45
	v_pk_fma_f32 v[42:43], v[46:47], v[48:49], v[50:51] op_sel_hi:[1,1,0]
	v_mul_f32_e32 v42, v52, v53
	v_mul_f32_e32 v45, v191, v45
	v_exp_f32_e32 v45, v45
	v_mul_f32_e32 v46, v42, v38
	v_pk_fma_f32 v[42:43], v[42:43], v[38:39], v[46:47] op_sel_hi:[1,1,0]
	v_add_f32_e32 v38, 1.0, v41
	v_fma_f32 v41, -v45, v45, 1.0
	v_max_f32_e32 v41, 0, v41
	v_rcp_f32_e32 v38, v38
	v_sqrt_f32_e32 v41, v41
	v_fma_f32 v42, v44, s100, v181
	v_exp_f32_e32 v46, v42
	v_mov_b32_e32 v44, v37
	v_mul_f32_e32 v42, v38, v41
	v_mul_f32_e32 v38, v42, v37
	v_add_f32_e32 v37, 1.0, v46
	v_rcp_f32_e32 v37, v37
	v_fma_f32 v40, v40, s100, v190
	v_exp_f32_e32 v40, v40
	v_mul_f32_e32 v41, v49, v51
	v_mul_f32_e32 v37, v191, v37
	v_exp_f32_e32 v37, v37
	v_add_f32_e32 v40, 1.0, v40
	v_rcp_f32_e32 v40, v40
	v_mul_f32_e32 v41, v39, v41
	v_fma_f32 v46, -v37, v37, 1.0
	v_max_f32_e32 v46, 0, v46
	v_sqrt_f32_e32 v46, v46
	v_pk_fma_f32 v[38:39], v[42:43], v[44:45], v[38:39] op_sel_hi:[1,1,0]
	v_mul_f32_e32 v41, v45, v41
	s_add_i32 s39, s39, 64
	v_mul_f32_e32 v38, v40, v46
	v_mul_f32_e32 v40, v39, v37
	v_pk_fma_f32 v[38:39], v[38:39], v[36:37], v[40:41] op_sel_hi:[1,1,0]
	v_mul_f32_e32 v37, v37, v41
	ds_bpermute_b32 v39, v126, v37
	ds_bpermute_b32 v40, v126, v38
	ds_bpermute_b32 v41, v125, v37
	ds_bpermute_b32 v42, v125, v38
	ds_bpermute_b32 v36, v124, v37
	ds_bpermute_b32 v43, v124, v38
	ds_bpermute_b32 v37, v122, v37
	s_waitcnt lgkmcnt(5)
	v_fmac_f32_e32 v40, 0, v39
	ds_bpermute_b32 v44, v122, v38
	s_waitcnt lgkmcnt(4)
	v_fmac_f32_e32 v42, v40, v41
	s_waitcnt lgkmcnt(3)
	v_mul_f32_e32 v40, v42, v36
	v_mul_f32_e32 v38, v39, v41
	s_waitcnt lgkmcnt(2)
	v_add_f32_e32 v39, v40, v43
	s_waitcnt lgkmcnt(1)
	v_pk_mul_f32 v[38:39], v[38:39], v[36:37]
	s_cmpk_eq_i32 s39, 0x100
	v_mul_f32_e32 v36, v38, v37
	s_waitcnt lgkmcnt(0)
	v_add_f32_e32 v107, v39, v44
	v_fmac_f32_e32 v107, v131, v36
	v_mul_f32_e32 v106, v106, v36
	s_cbranch_scc1 .LBB0_221
	v_mov_b32_e32 v131, v107
	s_branch .LBB0_187

; #define LAS __attribute__((address_space(3)))
; template <bool PASS2>
; __device__ __forceinline__ void lru_item(const Frame& F, const Args& a, int item) {
;     ...
;         for (int si = 0; si < 4; ++si) { const int s = dir ? 3 - si : si;
;             if (PASS2 && dir == 0) {
; #pragma unroll
;                 for (int i1 = 0; i1 < 4; ++i1)
; #pragma unroll
;                     for (int i2 = 0; i2 < 4; ++i2) { hf[0][i1][i2] = hf[1][i1][i2]; hf[1][i1][i2] = hf[2][i1][i2]; hf[2][i1][i2] = hf[3][i1][i2]; } }
;             f32x4 ar[4], ai[4], ax[4];
; #pragma unroll
;             for (int rt = 0; rt < 4; ++rt) { ar[rt] = (f32x4){0.f, 0.f, 0.f, 0.f}; ai[rt] = (f32x4){0.f, 0.f, 0.f, 0.f}; ax[rt] = (f32x4){0.f, 0.f, 0.f, 0.f};
; #pragma unroll
;                 for (int ks = 0; ks < 4; ++ks) { const bf16x8 xf = *(const LAS bf16x8*)(AT + (64 * s + 16 * rt + fr) * AT_PITCH + 64 * ks + 16 * fq);
;                     ar[rt] = __builtin_amdgcn_mfma_f32_16x16x32_bf16(xf, wrf[ks], ar[rt], 0, 0, 0); ai[rt] = __builtin_amdgcn_mfma_f32_16x16x32_bf16(xf, wif[ks], ai[rt], 0, 0, 0);
;                     if (ks == ks0) ax[rt] = __builtin_amdgcn_mfma_f32_16x16x32_bf16(xf, sel, ax[rt], 0, 0, 0); } }
.LBB0_708:
	v_mul_f32_e32 v243, 0x3fb8aa3b, v207
	s_mov_b32 s100, 0xbfb8aa3b
	v_mul_f32_e32 v211, 0xbfb8aa3b, v204
	v_mul_f32_e32 v241, 0xbfb8aa3b, v206
	v_add_u32_e32 v125, v209, v105
	v_add_u32_e32 v240, 0x11400, v125
	ds_read_b128 v[212:215], v240
	ds_read_b128 v[216:219], v240 offset:64
	ds_read_b128 v[220:223], v240 offset:128
	ds_read_b128 v[224:227], v240 offset:192
	ds_read_b128 v[228:231], v240 offset:4352
	ds_read_b128 v[232:235], v240 offset:4416
	ds_read_b128 v[236:239], v240 offset:4480
	ds_read_b128 v[244:247], v240 offset:4544
	ds_read_b128 v[248:251], v240 offset:8704
	ds_read_b128 v[252:255], v240 offset:8768
	v_mov_b32_e32 v182, v4
	v_mov_b32_e32 v179, v7
	v_mov_b32_e32 v180, v6
	v_mov_b32_e32 v181, v5
	v_mov_b32_e32 v174, v12
	v_cndmask_b32_e64 v12, 0, 1, s[36:37]
	v_mov_b32_e32 v173, v13
	v_mov_b32_e32 v175, v11
	v_mov_b32_e32 v176, v10
	v_mov_b32_e32 v177, v9
	v_mov_b32_e32 v178, v8
	s_waitcnt lgkmcnt(9)
	v_mfma_f32_16x16x32_bf16 v[8:11], v[212:215], v[36:39], 0
	v_cmp_ne_u32_e64 s[8:9], 1, v12
	s_mov_b32 s29, s28
	s_mov_b32 s30, s28
	v_mfma_f32_16x16x32_bf16 v[12:15], v[212:215], v[44:47], 0
	s_mov_b32 s31, s28
	v_mov_b64_e32 v[28:29], s[28:29]
	v_mov_b32_e32 v183, v132
	v_mov_b32_e32 v184, v131
	v_mov_b32_e32 v185, v146
	v_mov_b32_e32 v186, v145
	v_mov_b32_e32 v187, v143
	v_mov_b32_e32 v188, v133
	v_mov_b32_e32 v132, v198
	v_mov_b32_e32 v131, v200
	v_mov_b32_e32 v146, v202
	v_mov_b32_e32 v145, v203
	v_mov_b32_e32 v143, v205
	v_mov_b32_e32 v133, v124
	v_mov_b64_e32 v[30:31], s[30:31]
	s_andn2_b64 vcc, exec, s[36:37]
	s_cbranch_vccnz .LBB0_710
	v_mfma_f32_16x16x32_bf16 v[28:31], v[212:215], v[0:3], 0

; __device__ __forceinline__ float fsig(float x) { return __builtin_amdgcn_rcpf(1.0f + __expf(-x)); }
; template <bool PASS2>
; __device__ __forceinline__ void lru_item(const Frame& F, const Args& a, int item) {
;     ...
;             for (int e = 0; e < 16; ++e) { const int ee = dir ? 15 - e : e; const int rt = ee >> 2, j = ee & 3;
;                 const float rg = fsig(ar[rt][j] + ba), ig = fsig(ai[rt][j] + bi); const float la = logu * rg; const float av = __expf(la);
;                 const float mult = (t0 + tl0 + ee == tstart) ? 1.0f : __builtin_amdgcn_sqrtf(fmaxf(1.0f - av * av, 0.f)); const float bv = mult * ig * ax[rt][j];
;                 ar[rt][j] = av; ai[rt][j] = bv; B16 = av * B16 + bv; A16 = av * A16; }
.LBB0_740:
	v_fma_f32 v80, v80, s100, v211
	v_exp_f32_e32 v80, v80
	v_fma_f32 v81, v81, s100, v211
	v_exp_f32_e32 v81, v81
	v_add_f32_e32 v80, 1.0, v80
	v_rcp_f32_e32 v80, v80
	v_add_f32_e32 v81, 1.0, v81
	v_rcp_f32_e32 v81, v81
	v_mul_f32_e32 v80, v243, v80
	v_exp_f32_e32 v80, v80
	v_mul_f32_e32 v81, v243, v81
	v_fma_f32 v76, v76, s100, v241
	v_fma_f32 v85, -v80, v80, 1.0
	v_max_f32_e32 v85, 0, v85
	v_exp_f32_e32 v76, v76
	v_sqrt_f32_e32 v85, v85
	v_fma_f32 v77, v77, s100, v241
	v_exp_f32_e32 v81, v81
	v_exp_f32_e32 v77, v77
	v_add_u32_e32 v84, s49, v208
	v_cmp_ne_u32_e32 vcc, 0, v84
	v_add_f32_e32 v76, 1.0, v76
	v_rcp_f32_e32 v76, v76
	v_cndmask_b32_e32 v84, 1.0, v85, vcc
	v_fma_f32 v85, -v81, v81, 1.0
	v_add_f32_e32 v77, 1.0, v77
	v_max_f32_e32 v85, 0, v85
	v_rcp_f32_e32 v77, v77
	v_sqrt_f32_e32 v85, v85
	v_mul_f32_e32 v76, v76, v84
	v_mul_f32_e32 v189, v76, v28
	v_mul_f32_e32 v76, v77, v85
	v_mul_f32_e32 v190, v76, v29
	v_fma_f32 v29, v82, s100, v211
	v_exp_f32_e32 v29, v29
	v_add_f32_e32 v76, v206, v78
	v_fma_f32 v78, v83, s100, v211
	v_add_f32_e32 v29, 1.0, v29
	v_rcp_f32_e32 v29, v29
	v_exp_f32_e32 v78, v78
	v_mul_f32_e32 v76, 0xbfb8aa3b, v76
	v_exp_f32_e32 v76, v76
	v_mul_f32_e32 v29, v243, v29
	v_add_f32_e32 v78, 1.0, v78
	v_exp_f32_e32 v29, v29
	v_rcp_f32_e32 v78, v78
	v_add_f32_e32 v76, 1.0, v76
	v_rcp_f32_e32 v76, v76
	v_fma_f32 v82, -v29, v29, 1.0
	v_mul_f32_e32 v78, v243, v78
	v_max_f32_e32 v82, 0, v82
	v_sqrt_f32_e32 v82, v82
	v_fma_f32 v79, v79, s100, v241
	v_exp_f32_e32 v78, v78
	v_exp_f32_e32 v79, v79
	v_mul_f32_e32 v76, v76, v82
	v_mul_f32_e32 v191, v76, v30
	v_fma_f32 v82, -v78, v78, 1.0
	v_add_f32_e32 v79, 1.0, v79
	v_max_f32_e32 v82, 0, v82
	v_rcp_f32_e32 v79, v79
	v_sqrt_f32_e32 v82, v82
	v_fma_f32 v68, v68, s100, v241
	v_exp_f32_e32 v68, v68
	v_mul_f32_e32 v76, v79, v82
	v_mul_f32_e32 v193, v76, v31
	v_fma_f32 v31, v72, s100, v211
	v_exp_f32_e32 v31, v31
	v_fma_f32 v72, v73, s100, v211
	v_exp_f32_e32 v72, v72
	v_add_f32_e32 v31, 1.0, v31
	v_rcp_f32_e32 v31, v31
	v_add_f32_e32 v68, 1.0, v68
	v_add_f32_e32 v72, 1.0, v72
	v_rcp_f32_e32 v72, v72
	v_mul_f32_e32 v31, v243, v31
	v_exp_f32_e32 v31, v31
	v_mul_f32_e32 v72, v243, v72
	v_fma_f32 v73, -v31, v31, 1.0
	v_max_f32_e32 v73, 0, v73
	v_rcp_f32_e32 v68, v68
	v_sqrt_f32_e32 v73, v73
	v_fma_f32 v69, v69, s100, v241
	v_exp_f32_e32 v72, v72
	v_exp_f32_e32 v69, v69
	v_mul_f32_e32 v68, v68, v73
	v_fma_f32 v28, 0, v80, v189
	v_fma_f32 v73, -v72, v72, 1.0
	v_add_f32_e32 v69, 1.0, v69
	v_max_f32_e32 v73, 0, v73
	v_rcp_f32_e32 v69, v69
	v_sqrt_f32_e32 v73, v73
	v_fma_f32 v28, v81, v28, v190
	v_mul_f32_e32 v77, v80, v81
	v_fma_f32 v28, v29, v28, v191
	v_mul_f32_e32 v30, v29, v77
	v_fma_f32 v28, v78, v28, v193
	v_mul_f32_e32 v30, v78, v30
	v_mul_f32_e32 v194, v68, v20
	v_fma_f32 v20, v28, v31, v194
	v_mul_f32_e32 v28, v30, v31
	v_mul_f32_e32 v30, v69, v73
	v_mul_f32_e32 v195, v30, v21
	v_fma_f32 v21, v74, s100, v211
	v_exp_f32_e32 v21, v21
	v_fma_f32 v68, v75, s100, v211
	v_exp_f32_e32 v68, v68
	v_add_f32_e32 v21, 1.0, v21
	v_rcp_f32_e32 v21, v21
	v_add_f32_e32 v68, 1.0, v68
	v_fma_f32 v30, v70, s100, v241
	v_mul_f32_e32 v21, v243, v21
	v_exp_f32_e32 v21, v21
	v_rcp_f32_e32 v68, v68
	v_exp_f32_e32 v30, v30
	v_fma_f32 v69, -v21, v21, 1.0
	v_mul_f32_e32 v68, v243, v68
	v_add_f32_e32 v30, 1.0, v30
	v_max_f32_e32 v69, 0, v69
	v_fma_f32 v70, v71, s100, v241
	v_rcp_f32_e32 v30, v30
	v_sqrt_f32_e32 v69, v69
	v_exp_f32_e32 v70, v70
	v_exp_f32_e32 v68, v68
	v_mul_f32_e32 v28, v72, v28
	v_mul_f32_e32 v30, v30, v69
	v_add_f32_e32 v69, 1.0, v70
	v_fma_f32 v70, -v68, v68, 1.0
	v_max_f32_e32 v70, 0, v70
	v_rcp_f32_e32 v69, v69
	v_sqrt_f32_e32 v70, v70
	v_mul_f32_e32 v196, v30, v22
	v_mul_f32_e32 v22, v21, v28
	v_mul_f32_e32 v28, v69, v70
	v_mul_f32_e32 v197, v28, v23
	v_fma_f32 v23, v32, s100, v211
	v_exp_f32_e32 v23, v23
	v_fma_f32 v28, v33, s100, v211
	v_exp_f32_e32 v28, v28
	v_add_f32_e32 v23, 1.0, v23
	v_rcp_f32_e32 v23, v23
	v_fma_f32 v24, v24, s100, v241
	v_add_f32_e32 v28, 1.0, v28
	v_rcp_f32_e32 v28, v28
	v_mul_f32_e32 v23, v243, v23
	v_exp_f32_e32 v23, v23
	v_exp_f32_e32 v24, v24
	v_mul_f32_e32 v28, v243, v28
	v_fma_f32 v30, -v23, v23, 1.0
	v_add_f32_e32 v24, 1.0, v24
	v_max_f32_e32 v30, 0, v30
	v_rcp_f32_e32 v24, v24
	v_sqrt_f32_e32 v30, v30
	v_fma_f32 v25, v25, s100, v241
	v_exp_f32_e32 v28, v28
	v_exp_f32_e32 v25, v25
	v_mul_f32_e32 v24, v24, v30
	v_fma_f32 v20, v72, v20, v195
	v_fma_f32 v30, -v28, v28, 1.0
	v_add_f32_e32 v25, 1.0, v25
	v_max_f32_e32 v30, 0, v30
	v_rcp_f32_e32 v25, v25
	v_sqrt_f32_e32 v30, v30
	v_fma_f32 v20, v21, v20, v196
	v_fma_f32 v20, v68, v20, v197
	v_mul_f32_e32 v22, v68, v22
	v_mul_f32_e32 v199, v24, v8
	v_fma_f32 v8, v20, v23, v199
	v_mul_f32_e32 v20, v22, v23
	v_mul_f32_e32 v22, v25, v30
	v_mul_f32_e32 v201, v22, v9
	v_fma_f32 v9, v34, s100, v211
	v_exp_f32_e32 v9, v9
	v_fma_f32 v22, v26, s100, v241
	v_exp_f32_e32 v22, v22
	v_add_f32_e32 v9, 1.0, v9
	v_rcp_f32_e32 v9, v9
	v_add_f32_e32 v22, 1.0, v22
	v_rcp_f32_e32 v22, v22
	v_mul_f32_e32 v9, v243, v9
	v_exp_f32_e32 v24, v9
	v_fma_f32 v9, v35, s100, v211
	v_exp_f32_e32 v9, v9
	v_fma_f32 v25, -v24, v24, 1.0
	v_max_f32_e32 v25, 0, v25
; #define LAS __attribute__((address_space(3)))
; __device__ __forceinline__ unsigned cvt_pk_bf16(float lo, float hi) { unsigned r; asm volatile("v_cvt_pk_bf16_f32 %0, %1, %2" : "=v"(r) : "v"(lo), "v"(hi)); return r; }
; __device__ __forceinline__ float bf2f(unsigned short b) { return __uint_as_float(((unsigned)b) << 16); }
; __device__ __forceinline__ float fsig(float x) { return __builtin_amdgcn_rcpf(1.0f + __expf(-x)); }
; template <bool PASS2>
; __device__ __forceinline__ void lru_item(const Frame& F, const Args& a, int item) {
;     ...
;             for (int e = 0; e < 16; ++e) { const int ee = dir ? 15 - e : e; const int rt = ee >> 2, j = ee & 3;
;                 const float rg = fsig(ar[rt][j] + ba), ig = fsig(ai[rt][j] + bi); const float la = logu * rg; const float av = __expf(la);
;                 const float mult = (t0 + tl0 + ee == tstart) ? 1.0f : __builtin_amdgcn_sqrtf(fmaxf(1.0f - av * av, 0.f)); const float bv = mult * ig * ax[rt][j];
;                 ar[rt][j] = av; ai[rt][j] = bv; B16 = av * B16 + bv; A16 = av * A16; }
;             const int pos = dir ? 3 - fq : fq;
;             float PA = 1.f, PB = 0.f, QA = 1.f, QB = 0.f;
; #pragma unroll
;             for (int i = 0; i < 4; ++i) { const int k = dir ? 3 - i : i; const float Ak = __shfl(A16, fr + 16 * k), Bk = __shfl(B16, fr + 16 * k);
;                 if (i < pos) { PB = Ak * PB + Bk; PA = Ak * PA; }
;                 QB = Ak * QB + Bk; QA = Ak * QA; }
;             if (PASS2) {
;                 float h = PA * hc + PB;
; #pragma unroll
;                 for (int e = 0; e < 16; ++e) { const int ee = dir ? 15 - e : e; const int rt = ee >> 2, j = ee & 3; h = ar[rt][j] * h + ai[rt][j];
;                     if (dir == 0) hf[3][rt][j] = h;
;                     else { LAS unsigned short* yp = (LAS unsigned short*)(R0 + (tl0 + ee) * AT_PITCH + 2 * c); const float yb = bf2f(*yp);
;                         const float u2 = 1.5957691216057308f * (yb + 0.044715f * yb * yb * yb);
;                         const float y = (hf[3][rt][j] + h) * yb * fsig(u2);
;                         *yp = (unsigned short)(cvt_pk_bf16(y, 0.f) & 0xffffu); } }
;                 hc = QA * hc + QB;
	v_sqrt_f32_e32 v25, v25
	v_add_f32_e32 v9, 1.0, v9
	v_rcp_f32_e32 v9, v9
	v_fma_f32 v26, v27, s100, v241
	v_exp_f32_e32 v26, v26
	v_mul_f32_e32 v9, v243, v9
	v_exp_f32_e32 v27, v9
	v_mul_f32_e32 v9, v22, v25
	v_add_f32_e32 v22, 1.0, v26
	v_rcp_f32_e32 v22, v22
	v_fma_f32 v25, -v27, v27, 1.0
	v_max_f32_e32 v25, 0, v25
	v_sqrt_f32_e32 v25, v25
	v_mul_f32_e32 v198, v9, v10
	v_fma_f32 v13, v13, s100, v241
	v_exp_f32_e32 v13, v13
	v_mul_f32_e32 v10, v22, v25
	v_mul_f32_e32 v200, v10, v11
	v_fma_f32 v10, v16, s100, v211
	v_exp_f32_e32 v10, v10
	v_add_f32_e32 v11, v206, v12
	v_fma_f32 v12, v17, s100, v211
	v_add_f32_e32 v10, 1.0, v10
	v_rcp_f32_e32 v10, v10
	v_exp_f32_e32 v12, v12
	v_mul_f32_e32 v11, 0xbfb8aa3b, v11
	v_exp_f32_e32 v11, v11
	v_mul_f32_e32 v10, v243, v10
	v_add_f32_e32 v12, 1.0, v12
	v_exp_f32_e32 v10, v10
	v_rcp_f32_e32 v12, v12
	v_add_f32_e32 v11, 1.0, v11
	v_rcp_f32_e32 v11, v11
	v_fma_f32 v16, -v10, v10, 1.0
	v_mul_f32_e32 v12, v243, v12
	v_max_f32_e32 v16, 0, v16
	v_sqrt_f32_e32 v16, v16
	v_exp_f32_e32 v12, v12
	v_add_f32_e32 v13, 1.0, v13
	v_rcp_f32_e32 v13, v13
	v_mul_f32_e32 v11, v11, v16
	v_fma_f32 v16, -v12, v12, 1.0
	v_max_f32_e32 v16, 0, v16
	v_sqrt_f32_e32 v16, v16
	v_fma_f32 v8, v28, v8, v201
	v_mul_f32_e32 v20, v28, v20
	v_fma_f32 v8, v24, v8, v198
	v_mul_f32_e32 v9, v24, v20
	v_fma_f32 v8, v27, v8, v200
	v_mul_f32_e32 v9, v27, v9
	v_mul_f32_e32 v202, v11, v4
	v_fma_f32 v4, v8, v10, v202
	v_mul_f32_e32 v8, v9, v10
	v_mul_f32_e32 v9, v13, v16
	v_mul_f32_e32 v203, v9, v5
	v_fma_f32 v5, v18, s100, v211
	v_exp_f32_e32 v5, v5
	v_fma_f32 v9, v14, s100, v241
	v_exp_f32_e32 v9, v9
	v_add_f32_e32 v5, 1.0, v5
	v_rcp_f32_e32 v5, v5
	v_add_f32_e32 v9, 1.0, v9
	v_fma_f32 v14, v15, s100, v241
	v_mul_f32_e32 v5, v243, v5
	v_exp_f32_e32 v11, v5
	v_fma_f32 v5, v19, s100, v211
	v_exp_f32_e32 v5, v5
	v_fma_f32 v13, -v11, v11, 1.0
	v_max_f32_e32 v13, 0, v13
	v_rcp_f32_e32 v9, v9
	v_add_f32_e32 v5, 1.0, v5
	v_rcp_f32_e32 v5, v5
	v_sqrt_f32_e32 v13, v13
	v_exp_f32_e32 v14, v14
	v_fma_f32 v4, v12, v4, v203
	v_mul_f32_e32 v5, v243, v5
	v_exp_f32_e32 v5, v5
	v_mul_f32_e32 v9, v9, v13
	v_add_f32_e32 v13, 1.0, v14
	v_rcp_f32_e32 v13, v13
	v_fma_f32 v14, -v5, v5, 1.0
	v_max_f32_e32 v14, 0, v14
	v_sqrt_f32_e32 v14, v14
	v_mul_f32_e32 v8, v12, v8
	v_mul_f32_e32 v205, v9, v6
	v_fma_f32 v9, v11, v4, v205
	v_mul_f32_e32 v15, v11, v8
	v_mul_f32_e32 v8, v13, v14
	v_mov_b32_e32 v4, v7
	v_pk_mul_f32 v[124:125], v[8:9], v[4:5]
	s_add_i32 s49, s49, 64
	v_pk_fma_f32 v[6:7], v[8:9], v[4:5], v[124:125] op_sel:[0,0,1] op_sel_hi:[1,1,0]
	v_mul_f32_e32 v4, v5, v15
	ds_bpermute_b32 v7, v140, v4
	ds_bpermute_b32 v13, v140, v6
	ds_bpermute_b32 v16, v128, v4
	ds_bpermute_b32 v17, v128, v6
	ds_bpermute_b32 v8, v129, v4
	ds_bpermute_b32 v18, v129, v6
	s_waitcnt lgkmcnt(4)
	v_fmac_f32_e32 v13, 0, v7
	v_cndmask_b32_e64 v14, v7, 1.0, s[0:1]
	v_cndmask_b32_e64 v15, v13, 0, s[0:1]
	ds_bpermute_b32 v9, v130, v4
	s_waitcnt lgkmcnt(3)
	v_fma_f32 v4, v15, v16, v17
	v_mul_f32_e32 v19, v14, v16
	v_cndmask_b32_e64 v14, v14, v19, s[16:17]
	v_cndmask_b32_e64 v4, v15, v4, s[16:17]
	v_fmac_f32_e32 v17, v13, v16
	s_waitcnt lgkmcnt(1)
	v_fma_f32 v13, v4, v8, v18
	v_mul_f32_e32 v15, v14, v8
	v_cndmask_b32_e64 v14, v14, v15, s[4:5]
	v_cndmask_b32_e64 v4, v4, v13, s[4:5]
	v_fmac_f32_e32 v4, v210, v14
	v_fmac_f32_e32 v189, v80, v4
	v_fmac_f32_e32 v190, v81, v189
	v_fmac_f32_e32 v191, v29, v190
	v_fmac_f32_e32 v193, v78, v191
	v_fmac_f32_e32 v194, v31, v193
	v_fmac_f32_e32 v195, v72, v194
	v_fmac_f32_e32 v196, v21, v195
	v_fmac_f32_e32 v197, v68, v196
	v_fmac_f32_e32 v199, v23, v197
	v_fmac_f32_e32 v201, v28, v199
	v_fmac_f32_e32 v198, v24, v201
	v_fmac_f32_e32 v200, v27, v198
	ds_bpermute_b32 v6, v130, v6
	v_fmac_f32_e32 v202, v10, v200
	v_fmac_f32_e32 v203, v12, v202
	v_mul_f32_e32 v13, v17, v8
	v_fmac_f32_e32 v205, v11, v203
	v_fmac_f32_e32 v124, v5, v205
	v_mul_f32_e32 v4, v7, v16
	v_add_f32_e32 v5, v13, v18
	s_waitcnt lgkmcnt(1)
	v_pk_mul_f32 v[4:5], v[4:5], v[8:9]
	s_cmpk_lg_i32 s49, 0x100
	v_mul_f32_e32 v4, v4, v9
	s_waitcnt lgkmcnt(0)
	v_add_f32_e32 v14, v5, v6
	v_fmac_f32_e32 v14, v210, v4
	v_add_u32_e32 v209, 0x4400, v209
	s_cbranch_scc0 .LBB0_742
	v_mov_b32_e32 v4, v163
	v_mov_b32_e32 v5, v164
	v_mov_b32_e32 v6, v165
	v_mov_b32_e32 v7, v166
	v_mov_b32_e32 v8, v167
	v_mov_b32_e32 v9, v168
	v_mov_b32_e32 v10, v169
	v_mov_b32_e32 v11, v170
	v_mov_b32_e32 v12, v171
	v_mov_b32_e32 v13, v172
	v_mov_b32_e32 v147, v188
	v_mov_b32_e32 v148, v187
	v_mov_b32_e32 v149, v186
	v_mov_b32_e32 v150, v185
	v_mov_b32_e32 v151, v184
	v_mov_b32_e32 v152, v183
	v_mov_b32_e32 v153, v182
	v_mov_b32_e32 v154, v181
	v_mov_b32_e32 v155, v180
	v_mov_b32_e32 v156, v179
	v_mov_b32_e32 v157, v178
	v_mov_b32_e32 v158, v177
	v_mov_b32_e32 v159, v176
	v_mov_b32_e32 v160, v175
	v_mov_b32_e32 v161, v174
	v_mov_b32_e32 v162, v173
	v_mov_b32_e32 v163, v201
	v_mov_b32_e32 v164, v199
	v_mov_b32_e32 v165, v197
	v_mov_b32_e32 v166, v196
	v_mov_b32_e32 v167, v195
	v_mov_b32_e32 v168, v194
	v_mov_b32_e32 v169, v193
	v_mov_b32_e32 v170, v191
	v_mov_b32_e32 v171, v190
	v_mov_b32_e32 v172, v189
	v_mov_b32_e32 v210, v14
	s_branch .LBB0_708

; __device__ __forceinline__ float fsig(float x) { return __builtin_amdgcn_rcpf(1.0f + __expf(-x)); }
; template <bool PASS2>
; __device__ __forceinline__ void lru_item(const Frame& F, const Args& a, int item) {
;     ...
;             for (int e = 0; e < 16; ++e) { const int ee = dir ? 15 - e : e; const int rt = ee >> 2, j = ee & 3;
;                 const float rg = fsig(ar[rt][j] + ba), ig = fsig(ai[rt][j] + bi); const float la = logu * rg; const float av = __expf(la);
;                 const float mult = (t0 + tl0 + ee == tstart) ? 1.0f : __builtin_amdgcn_sqrtf(fmaxf(1.0f - av * av, 0.f)); const float bv = mult * ig * ax[rt][j];
;                 ar[rt][j] = av; ai[rt][j] = bv; B16 = av * B16 + bv; A16 = av * A16; }
.LBB0_745:
	s_nop 3
	v_fma_f32 v83, v83, s100, v211
	v_exp_f32_e32 v83, v83
	v_fma_f32 v79, v79, s100, v241
	v_exp_f32_e32 v79, v79
	v_add_f32_e32 v83, 1.0, v83
	v_rcp_f32_e32 v83, v83
	s_xor_b32 s3, s2, 0xc0
	v_add_f32_e32 v79, 1.0, v79
	v_mul_f32_e32 v83, v243, v83
	v_exp_f32_e32 v83, v83
	v_or_b32_e32 v84, s3, v105
	v_fma_f32 v82, v82, s100, v211
	v_rcp_f32_e32 v79, v79
	v_fma_f32 v86, -v83, v83, 1.0
	v_max_f32_e32 v86, 0, v86
	v_sqrt_f32_e32 v86, v86
	v_add_u32_e32 v85, s74, v84
	v_exp_f32_e32 v82, v82
	s_movk_i32 s3, 0xff0
	v_cmp_ne_u32_e32 vcc, s3, v85
	v_fma_f32 v81, v81, s100, v211
	v_cndmask_b32_e32 v85, 1.0, v86, vcc
	v_mul_f32_e32 v79, v79, v85
	v_mul_f32_e32 v75, v79, v75
	v_add_f32_e32 v79, 1.0, v82
	v_rcp_f32_e32 v79, v79
	v_exp_f32_e32 v81, v81
	v_fma_f32 v78, v78, s100, v241
	v_mul_f32_e32 v79, v243, v79
	v_add_f32_e32 v81, 1.0, v81
	v_exp_f32_e32 v79, v79
	v_rcp_f32_e32 v81, v81
	v_exp_f32_e32 v78, v78
	v_fma_f32 v85, -v79, v79, 1.0
	v_mul_f32_e32 v81, v243, v81
	v_add_f32_e32 v78, 1.0, v78
	v_max_f32_e32 v85, 0, v85
	v_rcp_f32_e32 v78, v78
	v_sqrt_f32_e32 v85, v85
	v_fma_f32 v77, v77, s100, v241
	v_exp_f32_e32 v81, v81
	v_exp_f32_e32 v77, v77
	v_mul_f32_e32 v78, v78, v85
	v_fma_f32 v82, 0, v83, v75
	v_fma_f32 v85, -v81, v81, 1.0
	v_add_f32_e32 v77, 1.0, v77
	v_max_f32_e32 v85, 0, v85
	v_rcp_f32_e32 v77, v77
	v_sqrt_f32_e32 v85, v85
	v_mul_f32_e32 v74, v78, v74
	v_fma_f32 v78, v79, v82, v74
	v_mul_f32_e32 v77, v77, v85
	v_mul_f32_e32 v73, v77, v73
	v_fma_f32 v77, v81, v78, v73
	v_fma_f32 v78, v80, s100, v211
	v_exp_f32_e32 v78, v78
	v_fma_f32 v71, v71, s100, v211
	v_exp_f32_e32 v71, v71
	v_add_f32_e32 v78, 1.0, v78
	v_rcp_f32_e32 v78, v78
	v_add_f32_e32 v71, 1.0, v71
	v_fma_f32 v76, v76, s100, v241
	v_rcp_f32_e32 v71, v71
	v_mul_f32_e32 v78, v243, v78
	v_exp_f32_e32 v78, v78
	v_exp_f32_e32 v76, v76
	v_fma_f32 v70, v70, s100, v211
	v_mul_f32_e32 v82, v83, v79
	v_exp_f32_e32 v70, v70
	v_mul_f32_e32 v80, v81, v82
	v_fma_f32 v82, -v78, v78, 1.0
	v_mul_f32_e32 v71, v243, v71
	v_add_f32_e32 v76, 1.0, v76
	v_max_f32_e32 v82, 0, v82
	v_rcp_f32_e32 v76, v76
	v_sqrt_f32_e32 v82, v82
	v_fma_f32 v67, v67, s100, v241
	v_exp_f32_e32 v71, v71
	v_exp_f32_e32 v67, v67
	v_add_f32_e32 v70, 1.0, v70
	v_rcp_f32_e32 v70, v70
	v_fma_f32 v69, v69, s100, v211
	v_exp_f32_e32 v69, v69
	v_mul_f32_e32 v76, v76, v82
	v_fma_f32 v82, -v71, v71, 1.0
	v_add_f32_e32 v67, 1.0, v67
	v_max_f32_e32 v82, 0, v82
	v_rcp_f32_e32 v67, v67
	v_sqrt_f32_e32 v82, v82
	v_mul_f32_e32 v70, v243, v70
	v_add_f32_e32 v69, 1.0, v69
	v_fma_f32 v66, v66, s100, v241
	v_exp_f32_e32 v70, v70
	v_rcp_f32_e32 v69, v69
	v_exp_f32_e32 v66, v66
	v_mul_f32_e32 v72, v76, v72
	v_mul_f32_e32 v67, v67, v82
	v_fma_f32 v76, v78, v77, v72
	v_mul_f32_e32 v77, v78, v80
	v_mul_f32_e32 v63, v67, v63
	v_fma_f32 v67, v71, v76, v63
	v_mul_f32_e32 v76, v71, v77
	v_fma_f32 v77, -v70, v70, 1.0
	v_mul_f32_e32 v69, v243, v69
	v_add_f32_e32 v66, 1.0, v66
	v_max_f32_e32 v77, 0, v77
	v_rcp_f32_e32 v66, v66
	v_sqrt_f32_e32 v77, v77
	v_fma_f32 v65, v65, s100, v241
	v_exp_f32_e32 v69, v69
	v_exp_f32_e32 v65, v65
	v_mul_f32_e32 v66, v66, v77
	v_mul_f32_e32 v62, v66, v62
	v_fma_f32 v77, -v69, v69, 1.0
	v_add_f32_e32 v65, 1.0, v65
	v_max_f32_e32 v77, 0, v77
	v_rcp_f32_e32 v65, v65
	v_sqrt_f32_e32 v77, v77
	v_fma_f32 v66, v70, v67, v62
	v_fma_f32 v59, v59, s100, v211
	v_mul_f32_e32 v65, v65, v77
	v_mul_f32_e32 v61, v65, v61
	v_fma_f32 v65, v69, v66, v61
	v_fma_f32 v66, v68, s100, v211
	v_exp_f32_e32 v66, v66
	v_exp_f32_e32 v59, v59
	v_fma_f32 v64, v64, s100, v241
	v_add_f32_e32 v66, 1.0, v66
	v_rcp_f32_e32 v66, v66
	v_add_f32_e32 v59, 1.0, v59
	v_rcp_f32_e32 v59, v59
	v_exp_f32_e32 v64, v64
	v_mul_f32_e32 v66, v243, v66
	v_exp_f32_e32 v66, v66
	v_mul_f32_e32 v59, v243, v59
	v_add_f32_e32 v64, 1.0, v64
	v_fma_f32 v68, -v66, v66, 1.0
	v_max_f32_e32 v68, 0, v68
	v_rcp_f32_e32 v64, v64
	v_sqrt_f32_e32 v68, v68
	v_fma_f32 v55, v55, s100, v241
	v_exp_f32_e32 v59, v59
	v_exp_f32_e32 v55, v55
	v_mul_f32_e32 v64, v64, v68
	v_mul_f32_e32 v67, v70, v76
	v_fma_f32 v68, -v59, v59, 1.0
	v_add_f32_e32 v55, 1.0, v55
	v_max_f32_e32 v68, 0, v68
	v_rcp_f32_e32 v55, v55
	v_sqrt_f32_e32 v68, v68
	v_mul_f32_e32 v67, v69, v67
	v_mul_f32_e32 v60, v64, v60
	v_fma_f32 v64, v66, v65, v60
	v_mul_f32_e32 v55, v55, v68
	v_mul_f32_e32 v65, v66, v67
	v_mul_f32_e32 v67, v55, v51
	v_fma_f32 v55, v58, s100, v211
	v_exp_f32_e32 v55, v55
	v_fma_f32 v51, v59, v64, v67
	v_fma_f32 v54, v54, s100, v241
	v_add_f32_e32 v55, 1.0, v55
	v_rcp_f32_e32 v55, v55
	v_exp_f32_e32 v54, v54
	v_mul_f32_e32 v58, v59, v65
	v_mul_f32_e32 v55, v243, v55
	v_exp_f32_e32 v64, v55
	v_fma_f32 v55, v57, s100, v211
	v_exp_f32_e32 v55, v55
	v_fma_f32 v53, v53, s100, v241
	v_exp_f32_e32 v53, v53
	v_fma_f32 v57, -v64, v64, 1.0
	v_add_f32_e32 v55, 1.0, v55
	v_rcp_f32_e32 v55, v55
	v_add_f32_e32 v54, 1.0, v54
	v_max_f32_e32 v57, 0, v57
	v_rcp_f32_e32 v54, v54
	v_mul_f32_e32 v55, v243, v55
	v_exp_f32_e32 v65, v55
	v_sqrt_f32_e32 v57, v57
	v_add_f32_e32 v53, 1.0, v53
	v_rcp_f32_e32 v53, v53
	v_fma_f32 v55, -v65, v65, 1.0
	v_max_f32_e32 v55, 0, v55
	v_sqrt_f32_e32 v55, v55
	v_mul_f32_e32 v54, v54, v57
	v_mul_f32_e32 v57, v54, v50
	v_fma_f32 v50, v64, v51, v57
	v_mul_f32_e32 v53, v53, v55
	v_mul_f32_e32 v51, v64, v58
	v_mul_f32_e32 v58, v53, v49
	v_fma_f32 v49, v65, v50, v58
	v_fma_f32 v50, v56, s100, v211
	v_exp_f32_e32 v50, v50
	v_fma_f32 v47, v47, s100, v211
	v_exp_f32_e32 v47, v47
	v_add_f32_e32 v50, 1.0, v50
	v_rcp_f32_e32 v50, v50
	v_add_f32_e32 v47, 1.0, v47
	v_fma_f32 v52, v52, s100, v241
	v_mul_f32_e32 v50, v243, v50
	v_exp_f32_e32 v56, v50
	v_rcp_f32_e32 v47, v47
; #define LAS __attribute__((address_space(3)))
; __device__ __forceinline__ unsigned cvt_pk_bf16(float lo, float hi) { unsigned r; asm volatile("v_cvt_pk_bf16_f32 %0, %1, %2" : "=v"(r) : "v"(lo), "v"(hi)); return r; }
; __device__ __forceinline__ float bf2f(unsigned short b) { return __uint_as_float(((unsigned)b) << 16); }
; __device__ __forceinline__ float fsig(float x) { return __builtin_amdgcn_rcpf(1.0f + __expf(-x)); }
; template <bool PASS2>
; __device__ __forceinline__ void lru_item(const Frame& F, const Args& a, int item) {
;     ...
;             for (int e = 0; e < 16; ++e) { const int ee = dir ? 15 - e : e; const int rt = ee >> 2, j = ee & 3;
;                 const float rg = fsig(ar[rt][j] + ba), ig = fsig(ai[rt][j] + bi); const float la = logu * rg; const float av = __expf(la);
;                 const float mult = (t0 + tl0 + ee == tstart) ? 1.0f : __builtin_amdgcn_sqrtf(fmaxf(1.0f - av * av, 0.f)); const float bv = mult * ig * ax[rt][j];
;                 ar[rt][j] = av; ai[rt][j] = bv; B16 = av * B16 + bv; A16 = av * A16; }
;             const int pos = dir ? 3 - fq : fq;
;             float PA = 1.f, PB = 0.f, QA = 1.f, QB = 0.f;
; #pragma unroll
;             for (int i = 0; i < 4; ++i) { const int k = dir ? 3 - i : i; const float Ak = __shfl(A16, fr + 16 * k), Bk = __shfl(B16, fr + 16 * k);
;                 if (i < pos) { PB = Ak * PB + Bk; PA = Ak * PA; }
;                 QB = Ak * QB + Bk; QA = Ak * QA; }
;             if (PASS2) {
;                 float h = PA * hc + PB;
; #pragma unroll
;                 for (int e = 0; e < 16; ++e) { const int ee = dir ? 15 - e : e; const int rt = ee >> 2, j = ee & 3; h = ar[rt][j] * h + ai[rt][j];
;                     if (dir == 0) hf[3][rt][j] = h;
;                     else { LAS unsigned short* yp = (LAS unsigned short*)(R0 + (tl0 + ee) * AT_PITCH + 2 * c); const float yb = bf2f(*yp);
;                         const float u2 = 1.5957691216057308f * (yb + 0.044715f * yb * yb * yb);
;                         const float y = (hf[3][rt][j] + h) * yb * fsig(u2);
;                         *yp = (unsigned short)(cvt_pk_bf16(y, 0.f) & 0xffffu); } }
	v_exp_f32_e32 v52, v52
	v_mul_f32_e32 v53, v65, v51
	v_fma_f32 v50, -v56, v56, 1.0
	v_mul_f32_e32 v47, v243, v47
	v_add_f32_e32 v51, 1.0, v52
	v_max_f32_e32 v50, 0, v50
	v_rcp_f32_e32 v51, v51
	v_sqrt_f32_e32 v50, v50
	v_fma_f32 v43, v43, s100, v241
	v_exp_f32_e32 v47, v47
	v_exp_f32_e32 v43, v43
	v_mul_f32_e32 v50, v51, v50
	v_mul_f32_e32 v68, v50, v48
	v_fma_f32 v51, -v47, v47, 1.0
	v_add_f32_e32 v43, 1.0, v43
	v_max_f32_e32 v51, 0, v51
	v_rcp_f32_e32 v43, v43
	v_sqrt_f32_e32 v52, v51
	v_fma_f32 v42, v42, s100, v241
	v_exp_f32_e32 v42, v42
	v_mul_f32_e32 v50, v43, v52
	v_fma_f32 v43, v46, s100, v211
	v_exp_f32_e32 v43, v43
	v_mov_b32_e32 v46, v39
	v_add_f32_e32 v42, 1.0, v42
	v_rcp_f32_e32 v42, v42
	v_add_f32_e32 v39, 1.0, v43
	v_rcp_f32_e32 v39, v39
	v_fma_f32 v51, v56, v49, v68
	v_fma_f32 v45, v45, s100, v211
	v_mul_f32_e32 v39, v243, v39
	v_exp_f32_e32 v39, v39
	v_pk_mul_f32 v[48:49], v[50:51], v[46:47]
	v_exp_f32_e32 v45, v45
	v_pk_fma_f32 v[50:51], v[50:51], v[46:47], v[48:49] op_sel_hi:[1,1,0]
	v_fma_f32 v43, -v39, v39, 1.0
	v_max_f32_e32 v43, 0, v43
	v_sqrt_f32_e32 v43, v43
	v_mul_f32_e32 v53, v56, v53
	v_mul_f32_e32 v46, v47, v53
	v_mul_f32_e32 v50, v42, v43
	v_pk_mul_f32 v[42:43], v[50:51], v[38:39]
	v_fma_f32 v44, v44, s100, v211
	v_pk_fma_f32 v[50:51], v[50:51], v[38:39], v[42:43] op_sel_hi:[1,1,0]
	v_add_f32_e32 v38, 1.0, v45
	v_rcp_f32_e32 v38, v38
	v_fma_f32 v41, v41, s100, v241
	v_exp_f32_e32 v41, v41
	v_mul_f32_e32 v38, v243, v38
	v_exp_f32_e32 v45, v38
	v_mul_f32_e32 v38, v39, v46
	v_exp_f32_e32 v46, v44
	v_mov_b32_e32 v44, v37
	v_fma_f32 v43, -v45, v45, 1.0
	v_add_f32_e32 v37, 1.0, v46
	v_rcp_f32_e32 v37, v37
	v_fma_f32 v40, v40, s100, v241
	v_add_f32_e32 v41, 1.0, v41
	v_max_f32_e32 v43, 0, v43
	v_mul_f32_e32 v37, v243, v37
	v_exp_f32_e32 v40, v40
	v_rcp_f32_e32 v41, v41
	v_sqrt_f32_e32 v43, v43
	v_exp_f32_e32 v37, v37
	v_add_f32_e32 v40, 1.0, v40
	v_mul_f32_e32 v38, v45, v38
	v_mul_f32_e32 v50, v41, v43
	v_rcp_f32_e32 v43, v40
	v_fma_f32 v40, -v37, v37, 1.0
	v_max_f32_e32 v40, 0, v40
	v_sqrt_f32_e32 v46, v40
	v_pk_mul_f32 v[40:41], v[50:51], v[44:45]
	s_add_i32 s2, s2, 64
	v_pk_fma_f32 v[52:53], v[50:51], v[44:45], v[40:41] op_sel_hi:[1,1,0]
	s_cmpk_lg_i32 s2, 0x100
	v_mul_f32_e32 v52, v43, v46
	v_pk_mul_f32 v[50:51], v[52:53], v[36:37]
	s_nop 0
	v_pk_fma_f32 v[54:55], v[52:53], v[36:37], v[50:51] op_sel:[0,0,1] op_sel_hi:[1,1,0]
	v_mad_u64_u32 v[52:53], s[30:31], v84, s50, v[120:121]
	v_mul_f32_e32 v36, v37, v38
	ds_read_u16 v38, v52 offset:4080
	ds_bpermute_b32 v41, v130, v36
	ds_bpermute_b32 v43, v130, v54
	ds_bpermute_b32 v49, v129, v36
	ds_bpermute_b32 v55, v129, v54
	s_waitcnt lgkmcnt(4)
	v_lshlrev_b32_e32 v51, 16, v38
	v_mul_f32_e32 v38, 0x3d372713, v51
	v_mul_f32_e32 v38, v38, v51
	v_fma_f32 v38, v38, v51, v51
	v_mul_f32_e32 v38, 0xc0135761, v38
	v_exp_f32_e32 v53, v38
	ds_bpermute_b32 v38, v128, v36
	ds_bpermute_b32 v76, v128, v54
	s_waitcnt lgkmcnt(4)
	v_fmac_f32_e32 v43, 0, v41
	v_cndmask_b32_e64 v44, v41, 1.0, s[4:5]
	v_cndmask_b32_e64 v46, v43, 0, s[4:5]
	s_waitcnt lgkmcnt(2)
	v_fma_f32 v77, v46, v49, v55
	v_mul_f32_e32 v80, v44, v49
	v_cndmask_b32_e64 v44, v44, v80, s[6:7]
	v_cndmask_b32_e64 v46, v46, v77, s[6:7]
	s_waitcnt lgkmcnt(0)
	v_fma_f32 v77, v46, v38, v76
	v_mul_f32_e32 v80, v44, v38
	v_add_f32_e32 v53, 1.0, v53
	v_cndmask_b32_e64 v44, v44, v80, s[0:1]
	v_cndmask_b32_e64 v46, v46, v77, s[0:1]
	v_rcp_f32_e32 v53, v53
	v_fmac_f32_e32 v46, v127, v44
	v_fmac_f32_e32 v75, v83, v46
	v_add_f32_e32 v44, v124, v75
	v_mul_f32_e32 v44, v44, v51
	v_mul_f32_e32 v44, v44, v53
	v_cvt_pk_bf16_f32 v44, v44, v97
	ds_read_u16 v46, v52 offset:3808
	ds_write_b16 v52, v44 offset:4080
	v_fmac_f32_e32 v74, v79, v75
	v_fmac_f32_e32 v73, v81, v74
	v_fmac_f32_e32 v72, v78, v73
	s_waitcnt lgkmcnt(1)
	v_lshlrev_b32_e32 v46, 16, v46
	v_mul_f32_e32 v51, 0x3d372713, v46
	v_mul_f32_e32 v51, v51, v46
	v_fma_f32 v51, v51, v46, v46
	v_mul_f32_e32 v51, 0xc0135761, v51
	v_exp_f32_e32 v51, v51
	v_fmac_f32_e32 v63, v71, v72
	v_fmac_f32_e32 v62, v70, v63
	v_fmac_f32_e32 v61, v69, v62
	v_add_f32_e32 v44, 1.0, v51
	v_rcp_f32_e32 v44, v44
	v_add_f32_e32 v51, v205, v74
	v_mul_f32_e32 v46, v51, v46
	v_fmac_f32_e32 v60, v66, v61
	v_mul_f32_e32 v44, v46, v44
	v_cvt_pk_bf16_f32 v44, v44, v97
	ds_read_u16 v46, v52 offset:3536
	ds_write_b16 v52, v44 offset:3808
	v_fmac_f32_e32 v67, v59, v60
	v_fmac_f32_e32 v57, v64, v67
	v_fmac_f32_e32 v58, v65, v57
	s_waitcnt lgkmcnt(1)
	v_lshlrev_b32_e32 v46, 16, v46
	v_mul_f32_e32 v51, 0x3d372713, v46
	v_mul_f32_e32 v51, v51, v46
	v_fma_f32 v51, v51, v46, v46
	v_mul_f32_e32 v51, 0xc0135761, v51
	v_exp_f32_e32 v51, v51
	v_fmac_f32_e32 v68, v56, v58
	v_fmac_f32_e32 v48, v47, v68
	v_add_f32_e32 v47, v193, v48
	v_add_f32_e32 v44, 1.0, v51
	v_rcp_f32_e32 v44, v44
	v_add_f32_e32 v51, v203, v73
	v_mul_f32_e32 v46, v51, v46
	v_fmac_f32_e32 v42, v39, v48
	v_mul_f32_e32 v44, v46, v44
	v_cvt_pk_bf16_f32 v44, v44, v97
	ds_read_u16 v46, v52 offset:3264
	ds_write_b16 v52, v44 offset:3536
	v_add_f32_e32 v39, v191, v42
	v_fmac_f32_e32 v40, v45, v42
	v_add_f32_e32 v42, v190, v40
	s_waitcnt lgkmcnt(1)
	v_lshlrev_b32_e32 v46, 16, v46
	v_mul_f32_e32 v51, 0x3d372713, v46
	v_mul_f32_e32 v51, v51, v46
	v_fma_f32 v51, v51, v46, v46
	v_mul_f32_e32 v51, 0xc0135761, v51
	v_exp_f32_e32 v51, v51
	v_fmac_f32_e32 v50, v37, v40
	v_add_f32_e32 v37, v189, v50
	ds_bpermute_b32 v45, v140, v54
	v_add_f32_e32 v44, 1.0, v51
	v_rcp_f32_e32 v44, v44
	v_add_f32_e32 v51, v202, v72
	v_mul_f32_e32 v46, v51, v46
	v_fmac_f32_e32 v55, v43, v49
	v_mul_f32_e32 v44, v46, v44
	v_cvt_pk_bf16_f32 v44, v44, v97
	ds_read_u16 v46, v52 offset:2992
	ds_write_b16 v52, v44 offset:3264
	v_mul_f32_e32 v43, v55, v38
	v_mov_b32_e32 v124, v133
	v_mov_b32_e32 v205, v143
	s_waitcnt lgkmcnt(1)
; #define LAS __attribute__((address_space(3)))
; __device__ __forceinline__ unsigned cvt_pk_bf16(float lo, float hi) { unsigned r; asm volatile("v_cvt_pk_bf16_f32 %0, %1, %2" : "=v"(r) : "v"(lo), "v"(hi)); return r; }
; __device__ __forceinline__ float bf2f(unsigned short b) { return __uint_as_float(((unsigned)b) << 16); }
; __device__ __forceinline__ float fsig(float x) { return __builtin_amdgcn_rcpf(1.0f + __expf(-x)); }
; template <bool PASS2>
; __device__ __forceinline__ void lru_item(const Frame& F, const Args& a, int item) {
;     ...
;                 float h = PA * hc + PB;
; #pragma unroll
;                 for (int e = 0; e < 16; ++e) { const int ee = dir ? 15 - e : e; const int rt = ee >> 2, j = ee & 3; h = ar[rt][j] * h + ai[rt][j];
;                     if (dir == 0) hf[3][rt][j] = h;
;                     else { LAS unsigned short* yp = (LAS unsigned short*)(R0 + (tl0 + ee) * AT_PITCH + 2 * c); const float yb = bf2f(*yp);
;                         const float u2 = 1.5957691216057308f * (yb + 0.044715f * yb * yb * yb);
;                         const float y = (hf[3][rt][j] + h) * yb * fsig(u2);
;                         *yp = (unsigned short)(cvt_pk_bf16(y, 0.f) & 0xffffu); } }
;                 hc = QA * hc + QB;
	v_lshlrev_b32_e32 v46, 16, v46
	v_mul_f32_e32 v51, 0x3d372713, v46
	v_mul_f32_e32 v51, v51, v46
	v_fma_f32 v51, v51, v46, v46
	v_mul_f32_e32 v51, 0xc0135761, v51
	v_exp_f32_e32 v51, v51
	v_mov_b32_e32 v203, v145
	v_mov_b32_e32 v202, v146
	v_mov_b32_e32 v193, v169
	v_add_f32_e32 v44, 1.0, v51
	v_rcp_f32_e32 v44, v44
	v_add_f32_e32 v51, v200, v63
	v_mul_f32_e32 v46, v51, v46
	v_mov_b32_e32 v200, v131
	v_mul_f32_e32 v44, v46, v44
	v_cvt_pk_bf16_f32 v44, v44, v97
	ds_read_u16 v46, v52 offset:2720
	ds_write_b16 v52, v44 offset:2992
	v_mov_b32_e32 v191, v170
	v_mov_b32_e32 v190, v171
	v_mov_b32_e32 v189, v172
	s_waitcnt lgkmcnt(1)
	v_lshlrev_b32_e32 v46, 16, v46
	v_mul_f32_e32 v51, 0x3d372713, v46
	v_mul_f32_e32 v51, v51, v46
	v_fma_f32 v51, v51, v46, v46
	v_mul_f32_e32 v51, 0xc0135761, v51
	v_exp_f32_e32 v51, v51
	v_mov_b32_e32 v133, v188
	v_mov_b32_e32 v143, v187
	v_mov_b32_e32 v145, v186
	v_add_f32_e32 v44, 1.0, v51
	v_rcp_f32_e32 v44, v44
	v_add_f32_e32 v51, v198, v62
	v_mul_f32_e32 v46, v51, v46
	v_mov_b32_e32 v198, v132
	v_mul_f32_e32 v44, v46, v44
	v_cvt_pk_bf16_f32 v44, v44, v97
	ds_read_u16 v46, v52 offset:2448
	ds_write_b16 v52, v44 offset:2720
	v_mov_b32_e32 v146, v185
	v_mov_b32_e32 v131, v184
	v_mov_b32_e32 v132, v183
	s_waitcnt lgkmcnt(1)
	v_lshlrev_b32_e32 v46, 16, v46
	v_mul_f32_e32 v51, 0x3d372713, v46
	v_mul_f32_e32 v51, v51, v46
	v_fma_f32 v51, v51, v46, v46
	v_mul_f32_e32 v51, 0xc0135761, v51
	v_exp_f32_e32 v51, v51
	v_mov_b32_e32 v169, v176
	v_mov_b32_e32 v170, v175
	v_mov_b32_e32 v171, v174
	v_add_f32_e32 v44, 1.0, v51
	v_rcp_f32_e32 v44, v44
	v_add_f32_e32 v51, v201, v61
	v_mul_f32_e32 v46, v51, v46
	v_mov_b32_e32 v201, v163
	v_mul_f32_e32 v44, v46, v44
	v_cvt_pk_bf16_f32 v44, v44, v97
	ds_read_u16 v46, v52 offset:2176
	ds_write_b16 v52, v44 offset:2448
	v_mov_b32_e32 v163, v182
	v_mov_b32_e32 v172, v173
	v_mov_b32_e32 v188, v147
	s_waitcnt lgkmcnt(1)
	v_lshlrev_b32_e32 v46, 16, v46
	v_mul_f32_e32 v51, 0x3d372713, v46
	v_mul_f32_e32 v51, v51, v46
	v_fma_f32 v51, v51, v46, v46
	v_mul_f32_e32 v51, 0xc0135761, v51
	v_exp_f32_e32 v51, v51
	v_mov_b32_e32 v187, v148
	v_mov_b32_e32 v186, v149
	v_mov_b32_e32 v185, v150
	v_add_f32_e32 v44, 1.0, v51
	v_rcp_f32_e32 v44, v44
	v_add_f32_e32 v51, v199, v60
	v_mul_f32_e32 v46, v51, v46
	v_mov_b32_e32 v199, v164
	v_mul_f32_e32 v44, v46, v44
	v_cvt_pk_bf16_f32 v44, v44, v97
	ds_read_u16 v46, v52 offset:1904
	ds_write_b16 v52, v44 offset:2176
	v_mov_b32_e32 v164, v181
	v_mov_b32_e32 v184, v151
	v_mov_b32_e32 v183, v152
	s_waitcnt lgkmcnt(1)
	v_lshlrev_b32_e32 v46, 16, v46
	v_mul_f32_e32 v51, 0x3d372713, v46
	v_mul_f32_e32 v51, v51, v46
	v_fma_f32 v51, v51, v46, v46
	v_mul_f32_e32 v51, 0xc0135761, v51
	v_exp_f32_e32 v51, v51
	v_mov_b32_e32 v182, v153
	v_mov_b32_e32 v181, v154
	v_mov_b32_e32 v176, v159
	v_add_f32_e32 v44, 1.0, v51
	v_rcp_f32_e32 v44, v44
	v_add_f32_e32 v51, v197, v67
	v_mul_f32_e32 v46, v51, v46
	v_mov_b32_e32 v197, v165
	v_mul_f32_e32 v44, v46, v44
	v_cvt_pk_bf16_f32 v44, v44, v97
	ds_read_u16 v46, v52 offset:1632
	ds_write_b16 v52, v44 offset:1904
	v_mov_b32_e32 v165, v180
	v_mov_b32_e32 v180, v155
	v_mov_b32_e32 v175, v160
	s_waitcnt lgkmcnt(1)
	v_lshlrev_b32_e32 v46, 16, v46
	v_mul_f32_e32 v51, 0x3d372713, v46
	v_mul_f32_e32 v51, v51, v46
	v_fma_f32 v51, v51, v46, v46
	v_mul_f32_e32 v51, 0xc0135761, v51
	v_exp_f32_e32 v51, v51
	v_mov_b32_e32 v174, v161
	v_mov_b32_e32 v173, v162
	v_add_f32_e32 v44, 1.0, v51
	v_rcp_f32_e32 v44, v44
	v_add_f32_e32 v51, v196, v57
	v_mul_f32_e32 v46, v51, v46
	v_mov_b32_e32 v196, v166
	v_mul_f32_e32 v44, v46, v44
	v_cvt_pk_bf16_f32 v44, v44, v97
	ds_read_u16 v46, v52 offset:1360
	ds_write_b16 v52, v44 offset:1632
	v_mov_b32_e32 v166, v179
	v_mov_b32_e32 v179, v156
	s_waitcnt lgkmcnt(1)
	v_lshlrev_b32_e32 v46, 16, v46
	v_mul_f32_e32 v51, 0x3d372713, v46
	v_mul_f32_e32 v51, v51, v46
	v_fma_f32 v51, v51, v46, v46
	v_mul_f32_e32 v51, 0xc0135761, v51
	v_exp_f32_e32 v51, v51
	s_nop 0
	v_add_f32_e32 v44, 1.0, v51
	v_rcp_f32_e32 v44, v44
	v_add_f32_e32 v51, v195, v58
	v_mul_f32_e32 v46, v51, v46
	v_mov_b32_e32 v195, v167
	v_mul_f32_e32 v44, v46, v44
	v_cvt_pk_bf16_f32 v44, v44, v97
	ds_read_u16 v46, v52 offset:1088
	ds_write_b16 v52, v44 offset:1360
	v_mov_b32_e32 v167, v178
	v_mov_b32_e32 v178, v157
	s_waitcnt lgkmcnt(1)
	v_lshlrev_b32_e32 v46, 16, v46
	v_mul_f32_e32 v51, 0x3d372713, v46
	v_mul_f32_e32 v51, v51, v46
	v_fma_f32 v51, v51, v46, v46
	v_mul_f32_e32 v51, 0xc0135761, v51
	v_exp_f32_e32 v51, v51
	s_nop 0
	v_add_f32_e32 v44, 1.0, v51
	v_rcp_f32_e32 v44, v44
	v_add_f32_e32 v51, v194, v68
	v_mul_f32_e32 v46, v51, v46
	v_mov_b32_e32 v194, v168
	v_mul_f32_e32 v44, v46, v44
	v_cvt_pk_bf16_f32 v44, v44, v97
	ds_read_u16 v46, v52 offset:816
	ds_write_b16 v52, v44 offset:1088
	v_mov_b32_e32 v168, v177
	v_mov_b32_e32 v177, v158
	s_waitcnt lgkmcnt(1)
	v_lshlrev_b32_e32 v46, 16, v46
	v_mul_f32_e32 v51, 0x3d372713, v46
	v_mul_f32_e32 v51, v51, v46
	v_fma_f32 v51, v51, v46, v46
	v_mul_f32_e32 v51, 0xc0135761, v51
	v_exp_f32_e32 v51, v51
	v_mul_f32_e32 v46, v47, v46
	v_add_f32_e32 v44, 1.0, v51
	v_rcp_f32_e32 v44, v44
	s_nop 0
	v_mul_f32_e32 v44, v46, v44
	v_cvt_pk_bf16_f32 v44, v44, v97
	ds_read_u16 v46, v52 offset:544
	ds_write_b16 v52, v44 offset:816
	s_waitcnt lgkmcnt(1)
	v_lshlrev_b32_e32 v46, 16, v46
	v_mul_f32_e32 v47, 0x3d372713, v46
	v_mul_f32_e32 v47, v47, v46
	v_fma_f32 v47, v47, v46, v46
	v_mul_f32_e32 v47, 0xc0135761, v47
	v_exp_f32_e32 v47, v47
	v_mul_f32_e32 v39, v39, v46
	v_add_f32_e32 v44, 1.0, v47
	v_rcp_f32_e32 v44, v44
	s_nop 0
	v_mul_f32_e32 v39, v39, v44
	v_cvt_pk_bf16_f32 v39, v39, v97
	ds_read_u16 v44, v52 offset:272
	ds_write_b16 v52, v39 offset:544
	s_waitcnt lgkmcnt(1)
	v_lshlrev_b32_e32 v44, 16, v44
	v_mul_f32_e32 v46, 0x3d372713, v44
	v_mul_f32_e32 v46, v46, v44
	v_fma_f32 v46, v46, v44, v44
	v_mul_f32_e32 v46, 0xc0135761, v46
	v_exp_f32_e32 v46, v46
	v_mul_f32_e32 v42, v42, v44
	v_add_f32_e32 v39, 1.0, v46
	v_rcp_f32_e32 v39, v39
	s_nop 0
	v_mul_f32_e32 v39, v42, v39
	v_cvt_pk_bf16_f32 v42, v39, v97
	ds_read_u16 v44, v52
	ds_bpermute_b32 v39, v140, v36
	ds_write_b16 v52, v42 offset:272
	s_waitcnt lgkmcnt(2)
	v_lshlrev_b32_e32 v36, 16, v44
	v_mul_f32_e32 v44, 0x3d372713, v36
	v_mul_f32_e32 v44, v44, v36
	v_fma_f32 v44, v44, v36, v36
	v_mul_f32_e32 v44, 0xc0135761, v44
	v_exp_f32_e32 v44, v44
	v_mul_f32_e32 v36, v37, v36
	v_add_f32_e32 v37, v43, v76
	v_add_f32_e32 v42, 1.0, v44
	v_rcp_f32_e32 v42, v42
	s_nop 0
	v_mul_f32_e32 v36, v36, v42
	v_cvt_pk_bf16_f32 v36, v36, v97
	ds_write_b16 v52, v36
	v_mul_f32_e32 v36, v41, v49
	s_waitcnt lgkmcnt(2)
	v_pk_mul_f32 v[36:37], v[36:37], v[38:39]
	s_nop 0
	v_mul_f32_e32 v36, v36, v39
	v_add_f32_e32 v37, v37, v45
	v_fmac_f32_e32 v37, v127, v36
	v_mov_b32_e32 v127, v37
	s_cbranch_scc0 .LBB0_698
; #define LAS __attribute__((address_space(3)))
; template <bool PASS2>
; __device__ __forceinline__ void lru_item(const Frame& F, const Args& a, int item) {
;     ...
;         for (int si = 0; si < 4; ++si) { const int s = dir ? 3 - si : si;
;             if (PASS2 && dir == 0) {
; #pragma unroll
;                 for (int i1 = 0; i1 < 4; ++i1)
; #pragma unroll
;                     for (int i2 = 0; i2 < 4; ++i2) { hf[0][i1][i2] = hf[1][i1][i2]; hf[1][i1][i2] = hf[2][i1][i2]; hf[2][i1][i2] = hf[3][i1][i2]; } }
;             f32x4 ar[4], ai[4], ax[4];
; #pragma unroll
;             for (int rt = 0; rt < 4; ++rt) { ar[rt] = (f32x4){0.f, 0.f, 0.f, 0.f}; ai[rt] = (f32x4){0.f, 0.f, 0.f, 0.f}; ax[rt] = (f32x4){0.f, 0.f, 0.f, 0.f};
; #pragma unroll
;                 for (int ks = 0; ks < 4; ++ks) { const bf16x8 xf = *(const LAS bf16x8*)(AT + (64 * s + 16 * rt + fr) * AT_PITCH + 64 * ks + 16 * fq);
;                     ar[rt] = __builtin_amdgcn_mfma_f32_16x16x32_bf16(xf, wrf[ks], ar[rt], 0, 0, 0); ai[rt] = __builtin_amdgcn_mfma_f32_16x16x32_bf16(xf, wif[ks], ai[rt], 0, 0, 0);
;                     if (ks == ks0) ax[rt] = __builtin_amdgcn_mfma_f32_16x16x32_bf16(xf, sel, ax[rt], 0, 0, 0); } }
.LBB0_746:
	v_mul_f32_e32 v243, 0x3fb8aa3b, v126
	s_mov_b32 s100, 0xbfb8aa3b
	v_mul_f32_e32 v211, 0xbfb8aa3b, v125
	v_mul_f32_e32 v241, 0xbfb8aa3b, v204
	v_bitop3_b32 v36, s2, v95, v141 bitop3:0xde
	v_mul_lo_u32 v36, v36, s50
	v_add_u32_e32 v206, v107, v36
	ds_read_b128 v[212:215], v206
	ds_read_b128 v[216:219], v206 offset:64
	ds_read_b128 v[220:223], v206 offset:128
	ds_read_b128 v[224:227], v206 offset:192
	ds_read_b128 v[228:231], v206 offset:4352
	ds_read_b128 v[232:235], v206 offset:4416
	ds_read_b128 v[236:239], v206 offset:4480
	ds_read_b128 v[244:247], v206 offset:4544
	ds_read_b128 v[248:251], v206 offset:8704
	ds_read_b128 v[252:255], v206 offset:8768
	s_mov_b32 s30, s28
	s_mov_b32 s31, s28
	s_mov_b32 s29, s28
	v_mov_b64_e32 v[38:39], s[30:31]
	s_and_b64 vcc, exec, s[8:9]
	v_mov_b64_e32 v[36:37], s[28:29]
	s_waitcnt lgkmcnt(9)
	v_mfma_f32_16x16x32_bf16 v[44:47], v[212:215], v[32:35], 0
	v_mfma_f32_16x16x32_bf16 v[48:51], v[212:215], v[20:23], 0
	s_cbranch_vccnz .LBB0_748
	v_mfma_f32_16x16x32_bf16 v[36:39], v[212:215], v[0:3], 0

; #define LAS __attribute__((address_space(3)))
; template <bool PASS2>
; __device__ __forceinline__ void lru_item(const Frame& F, const Args& a, int item) {
;     ...
;         for (int si = 0; si < 4; ++si) { const int s = dir ? 3 - si : si;
;             if (PASS2 && dir == 0) {
; #pragma unroll
;                 for (int i1 = 0; i1 < 4; ++i1)
; #pragma unroll
;                     for (int i2 = 0; i2 < 4; ++i2) { hf[0][i1][i2] = hf[1][i1][i2]; hf[1][i1][i2] = hf[2][i1][i2]; hf[2][i1][i2] = hf[3][i1][i2]; } }
;             f32x4 ar[4], ai[4], ax[4];
; #pragma unroll
;             for (int rt = 0; rt < 4; ++rt) { ar[rt] = (f32x4){0.f, 0.f, 0.f, 0.f}; ai[rt] = (f32x4){0.f, 0.f, 0.f, 0.f}; ax[rt] = (f32x4){0.f, 0.f, 0.f, 0.f};
; #pragma unroll
;                 for (int ks = 0; ks < 4; ++ks) { const bf16x8 xf = *(const LAS bf16x8*)(AT + (64 * s + 16 * rt + fr) * AT_PITCH + 64 * ks + 16 * fq);
;                     ar[rt] = __builtin_amdgcn_mfma_f32_16x16x32_bf16(xf, wrf[ks], ar[rt], 0, 0, 0); ai[rt] = __builtin_amdgcn_mfma_f32_16x16x32_bf16(xf, wif[ks], ai[rt], 0, 0, 0);
;                     if (ks == ks0) ax[rt] = __builtin_amdgcn_mfma_f32_16x16x32_bf16(xf, sel, ax[rt], 0, 0, 0); } }
.LBB0_827:
	v_mul_f32_e32 v243, 0x3fb8aa3b, v207
	s_mov_b32 s100, 0xbfb8aa3b
	v_mul_f32_e32 v211, 0xbfb8aa3b, v204
	v_mul_f32_e32 v241, 0xbfb8aa3b, v206
	v_add_u32_e32 v125, v209, v103
	v_add_u32_e32 v240, 0x11400, v125
	ds_read_b128 v[212:215], v240
	ds_read_b128 v[216:219], v240 offset:64
	ds_read_b128 v[220:223], v240 offset:128
	ds_read_b128 v[224:227], v240 offset:192
	ds_read_b128 v[228:231], v240 offset:4352
	ds_read_b128 v[232:235], v240 offset:4416
	ds_read_b128 v[236:239], v240 offset:4480
	ds_read_b128 v[244:247], v240 offset:4544
	ds_read_b128 v[248:251], v240 offset:8704
	ds_read_b128 v[252:255], v240 offset:8768
	v_mov_b32_e32 v182, v36
	v_mov_b32_e32 v179, v39
	v_mov_b32_e32 v180, v38
	v_mov_b32_e32 v181, v37
	v_mov_b32_e32 v174, v44
	v_cndmask_b32_e64 v44, 0, 1, s[2:3]
	v_mov_b32_e32 v173, v45
	v_mov_b32_e32 v175, v43
	v_mov_b32_e32 v176, v42
	v_mov_b32_e32 v177, v41
	v_mov_b32_e32 v178, v40
	s_waitcnt lgkmcnt(9)
	v_mfma_f32_16x16x32_bf16 v[40:43], v[212:215], v[4:7], 0
	v_cmp_ne_u32_e64 s[8:9], 1, v44
	s_mov_b32 s30, s28
	s_mov_b32 s31, s28
	v_mfma_f32_16x16x32_bf16 v[44:47], v[212:215], v[12:15], 0
	s_mov_b32 s29, s28
	v_mov_b64_e32 v[62:63], s[30:31]
	v_mov_b32_e32 v183, v132
	v_mov_b32_e32 v184, v131
	v_mov_b32_e32 v185, v146
	v_mov_b32_e32 v186, v143
	v_mov_b32_e32 v187, v142
	v_mov_b32_e32 v188, v133
	v_mov_b32_e32 v132, v198
	v_mov_b32_e32 v131, v200
	v_mov_b32_e32 v146, v202
	v_mov_b32_e32 v143, v203
	v_mov_b32_e32 v142, v205
	v_mov_b32_e32 v133, v124
	v_mov_b64_e32 v[60:61], s[28:29]
	s_andn2_b64 vcc, exec, s[2:3]
	s_cbranch_vccnz .LBB0_829
	v_mfma_f32_16x16x32_bf16 v[60:63], v[212:215], v[0:3], 0

; __device__ __forceinline__ float fsig(float x) { return __builtin_amdgcn_rcpf(1.0f + __expf(-x)); }
; template <bool PASS2>
; __device__ __forceinline__ void lru_item(const Frame& F, const Args& a, int item) {
;     ...
;             for (int e = 0; e < 16; ++e) { const int ee = dir ? 15 - e : e; const int rt = ee >> 2, j = ee & 3;
;                 const float rg = fsig(ar[rt][j] + ba), ig = fsig(ai[rt][j] + bi); const float la = logu * rg; const float av = __expf(la);
;                 const float mult = (t0 + tl0 + ee == tstart) ? 1.0f : __builtin_amdgcn_sqrtf(fmaxf(1.0f - av * av, 0.f)); const float bv = mult * ig * ax[rt][j];
;                 ar[rt][j] = av; ai[rt][j] = bv; B16 = av * B16 + bv; A16 = av * A16; }
.LBB0_859:
	v_fma_f32 v80, v80, s100, v211
	v_exp_f32_e32 v80, v80
	v_fma_f32 v81, v81, s100, v211
	v_exp_f32_e32 v81, v81
	v_add_f32_e32 v80, 1.0, v80
	v_rcp_f32_e32 v80, v80
	v_add_f32_e32 v81, 1.0, v81
	v_rcp_f32_e32 v81, v81
	v_mul_f32_e32 v80, v243, v80
	v_exp_f32_e32 v80, v80
	v_mul_f32_e32 v81, v243, v81
	v_fma_f32 v76, v76, s100, v241
	v_fma_f32 v85, -v80, v80, 1.0
	v_max_f32_e32 v85, 0, v85
	v_exp_f32_e32 v76, v76
	v_sqrt_f32_e32 v85, v85
	v_fma_f32 v77, v77, s100, v241
	v_exp_f32_e32 v81, v81
	v_exp_f32_e32 v77, v77
	v_add_u32_e32 v84, s82, v208
	v_cmp_ne_u32_e32 vcc, 0, v84
	v_add_f32_e32 v76, 1.0, v76
	v_rcp_f32_e32 v76, v76
	v_cndmask_b32_e32 v84, 1.0, v85, vcc
	v_fma_f32 v85, -v81, v81, 1.0
	v_add_f32_e32 v77, 1.0, v77
	v_max_f32_e32 v85, 0, v85
	v_rcp_f32_e32 v77, v77
	v_sqrt_f32_e32 v85, v85
	v_mul_f32_e32 v76, v76, v84
	v_mul_f32_e32 v189, v76, v60
	v_mul_f32_e32 v76, v77, v85
	v_mul_f32_e32 v190, v76, v61
	v_fma_f32 v61, v82, s100, v211
	v_exp_f32_e32 v61, v61
	v_add_f32_e32 v76, v206, v78
	v_fma_f32 v78, v83, s100, v211
	v_add_f32_e32 v61, 1.0, v61
	v_rcp_f32_e32 v61, v61
	v_exp_f32_e32 v78, v78
	v_mul_f32_e32 v76, 0xbfb8aa3b, v76
	v_exp_f32_e32 v76, v76
	v_mul_f32_e32 v61, v243, v61
	v_add_f32_e32 v78, 1.0, v78
	v_exp_f32_e32 v61, v61
	v_rcp_f32_e32 v78, v78
	v_add_f32_e32 v76, 1.0, v76
	v_rcp_f32_e32 v76, v76
	v_fma_f32 v82, -v61, v61, 1.0
	v_mul_f32_e32 v78, v243, v78
	v_max_f32_e32 v82, 0, v82
	v_sqrt_f32_e32 v82, v82
	v_fma_f32 v79, v79, s100, v241
	v_exp_f32_e32 v78, v78
	v_exp_f32_e32 v79, v79
	v_mul_f32_e32 v76, v76, v82
	v_mul_f32_e32 v191, v76, v62
	v_fma_f32 v82, -v78, v78, 1.0
	v_add_f32_e32 v79, 1.0, v79
	v_max_f32_e32 v82, 0, v82
	v_rcp_f32_e32 v79, v79
	v_sqrt_f32_e32 v82, v82
	v_fma_f32 v68, v68, s100, v241
	v_exp_f32_e32 v68, v68
	v_mul_f32_e32 v76, v79, v82
	v_mul_f32_e32 v193, v76, v63
	v_fma_f32 v63, v72, s100, v211
	v_exp_f32_e32 v63, v63
	v_fma_f32 v72, v73, s100, v211
	v_exp_f32_e32 v72, v72
	v_add_f32_e32 v63, 1.0, v63
	v_rcp_f32_e32 v63, v63
	v_add_f32_e32 v68, 1.0, v68
	v_add_f32_e32 v72, 1.0, v72
	v_rcp_f32_e32 v72, v72
	v_mul_f32_e32 v63, v243, v63
	v_exp_f32_e32 v63, v63
	v_mul_f32_e32 v72, v243, v72
	v_fma_f32 v73, -v63, v63, 1.0
	v_max_f32_e32 v73, 0, v73
	v_rcp_f32_e32 v68, v68
	v_sqrt_f32_e32 v73, v73
	v_fma_f32 v69, v69, s100, v241
	v_exp_f32_e32 v72, v72
	v_exp_f32_e32 v69, v69
	v_mul_f32_e32 v68, v68, v73
	v_fma_f32 v60, 0, v80, v189
	v_fma_f32 v73, -v72, v72, 1.0
	v_add_f32_e32 v69, 1.0, v69
	v_max_f32_e32 v73, 0, v73
	v_rcp_f32_e32 v69, v69
	v_sqrt_f32_e32 v73, v73
	v_fma_f32 v60, v81, v60, v190
	v_mul_f32_e32 v77, v80, v81
	v_fma_f32 v60, v61, v60, v191
	v_mul_f32_e32 v62, v61, v77
	v_fma_f32 v60, v78, v60, v193
	v_mul_f32_e32 v62, v78, v62
	v_mul_f32_e32 v194, v68, v52
	v_fma_f32 v52, v60, v63, v194
	v_mul_f32_e32 v60, v62, v63
	v_mul_f32_e32 v62, v69, v73
	v_mul_f32_e32 v195, v62, v53
	v_fma_f32 v53, v74, s100, v211
	v_exp_f32_e32 v53, v53
	v_fma_f32 v68, v75, s100, v211
	v_exp_f32_e32 v68, v68
	v_add_f32_e32 v53, 1.0, v53
	v_rcp_f32_e32 v53, v53
	v_add_f32_e32 v68, 1.0, v68
	v_fma_f32 v62, v70, s100, v241
	v_mul_f32_e32 v53, v243, v53
	v_exp_f32_e32 v53, v53
	v_rcp_f32_e32 v68, v68
	v_exp_f32_e32 v62, v62
	v_fma_f32 v69, -v53, v53, 1.0
	v_mul_f32_e32 v68, v243, v68
	v_add_f32_e32 v62, 1.0, v62
	v_max_f32_e32 v69, 0, v69
	v_fma_f32 v70, v71, s100, v241
	v_rcp_f32_e32 v62, v62
	v_sqrt_f32_e32 v69, v69
	v_exp_f32_e32 v70, v70
	v_exp_f32_e32 v68, v68
	v_mul_f32_e32 v60, v72, v60
	v_mul_f32_e32 v62, v62, v69
	v_add_f32_e32 v69, 1.0, v70
	v_fma_f32 v70, -v68, v68, 1.0
	v_max_f32_e32 v70, 0, v70
	v_rcp_f32_e32 v69, v69
	v_sqrt_f32_e32 v70, v70
	v_mul_f32_e32 v196, v62, v54
	v_mul_f32_e32 v54, v53, v60
	v_mul_f32_e32 v60, v69, v70
	v_mul_f32_e32 v197, v60, v55
	v_fma_f32 v55, v64, s100, v211
	v_exp_f32_e32 v55, v55
	v_fma_f32 v60, v65, s100, v211
	v_exp_f32_e32 v60, v60
	v_add_f32_e32 v55, 1.0, v55
	v_rcp_f32_e32 v55, v55
	v_fma_f32 v56, v56, s100, v241
	v_add_f32_e32 v60, 1.0, v60
	v_rcp_f32_e32 v60, v60
	v_mul_f32_e32 v55, v243, v55
	v_exp_f32_e32 v55, v55
	v_exp_f32_e32 v56, v56
	v_mul_f32_e32 v60, v243, v60
	v_fma_f32 v62, -v55, v55, 1.0
	v_add_f32_e32 v56, 1.0, v56
	v_max_f32_e32 v62, 0, v62
	v_rcp_f32_e32 v56, v56
	v_sqrt_f32_e32 v62, v62
	v_fma_f32 v57, v57, s100, v241
	v_exp_f32_e32 v60, v60
	v_exp_f32_e32 v57, v57
	v_mul_f32_e32 v56, v56, v62
	v_fma_f32 v52, v72, v52, v195
	v_fma_f32 v62, -v60, v60, 1.0
	v_add_f32_e32 v57, 1.0, v57
	v_max_f32_e32 v62, 0, v62
	v_rcp_f32_e32 v57, v57
	v_sqrt_f32_e32 v62, v62
	v_fma_f32 v52, v53, v52, v196
	v_fma_f32 v52, v68, v52, v197
	v_mul_f32_e32 v54, v68, v54
	v_mul_f32_e32 v199, v56, v40
	v_fma_f32 v40, v52, v55, v199
	v_mul_f32_e32 v52, v54, v55
	v_mul_f32_e32 v54, v57, v62
	v_mul_f32_e32 v201, v54, v41
	v_fma_f32 v41, v66, s100, v211
	v_exp_f32_e32 v41, v41
	v_fma_f32 v54, v58, s100, v241
	v_exp_f32_e32 v54, v54
	v_add_f32_e32 v41, 1.0, v41
	v_rcp_f32_e32 v41, v41
	v_add_f32_e32 v54, 1.0, v54
	v_rcp_f32_e32 v54, v54
	v_mul_f32_e32 v41, v243, v41
	v_exp_f32_e32 v56, v41
	v_fma_f32 v41, v67, s100, v211
	v_exp_f32_e32 v41, v41
	v_fma_f32 v57, -v56, v56, 1.0
	v_max_f32_e32 v57, 0, v57
	v_sqrt_f32_e32 v57, v57
	v_add_f32_e32 v41, 1.0, v41
; #define LAS __attribute__((address_space(3)))
; __device__ __forceinline__ unsigned cvt_pk_bf16(float lo, float hi) { unsigned r; asm volatile("v_cvt_pk_bf16_f32 %0, %1, %2" : "=v"(r) : "v"(lo), "v"(hi)); return r; }
; __device__ __forceinline__ float bf2f(unsigned short b) { return __uint_as_float(((unsigned)b) << 16); }
; __device__ __forceinline__ float fsig(float x) { return __builtin_amdgcn_rcpf(1.0f + __expf(-x)); }
; template <bool PASS2>
; __device__ __forceinline__ void lru_item(const Frame& F, const Args& a, int item) {
;     ...
;             for (int e = 0; e < 16; ++e) { const int ee = dir ? 15 - e : e; const int rt = ee >> 2, j = ee & 3;
;                 const float rg = fsig(ar[rt][j] + ba), ig = fsig(ai[rt][j] + bi); const float la = logu * rg; const float av = __expf(la);
;                 const float mult = (t0 + tl0 + ee == tstart) ? 1.0f : __builtin_amdgcn_sqrtf(fmaxf(1.0f - av * av, 0.f)); const float bv = mult * ig * ax[rt][j];
;                 ar[rt][j] = av; ai[rt][j] = bv; B16 = av * B16 + bv; A16 = av * A16; }
;             const int pos = dir ? 3 - fq : fq;
;             float PA = 1.f, PB = 0.f, QA = 1.f, QB = 0.f;
; #pragma unroll
;             for (int i = 0; i < 4; ++i) { const int k = dir ? 3 - i : i; const float Ak = __shfl(A16, fr + 16 * k), Bk = __shfl(B16, fr + 16 * k);
;                 if (i < pos) { PB = Ak * PB + Bk; PA = Ak * PA; }
;                 QB = Ak * QB + Bk; QA = Ak * QA; }
;             if (PASS2) {
;                 float h = PA * hc + PB;
; #pragma unroll
;                 for (int e = 0; e < 16; ++e) { const int ee = dir ? 15 - e : e; const int rt = ee >> 2, j = ee & 3; h = ar[rt][j] * h + ai[rt][j];
;                     if (dir == 0) hf[3][rt][j] = h;
;                     else { LAS unsigned short* yp = (LAS unsigned short*)(R0 + (tl0 + ee) * AT_PITCH + 2 * c); const float yb = bf2f(*yp);
;                         const float u2 = 1.5957691216057308f * (yb + 0.044715f * yb * yb * yb);
;                         const float y = (hf[3][rt][j] + h) * yb * fsig(u2);
;                         *yp = (unsigned short)(cvt_pk_bf16(y, 0.f) & 0xffffu); } }
;                 hc = QA * hc + QB;
	v_rcp_f32_e32 v41, v41
	v_fma_f32 v58, v59, s100, v241
	v_exp_f32_e32 v58, v58
	v_mul_f32_e32 v41, v243, v41
	v_exp_f32_e32 v59, v41
	v_mul_f32_e32 v41, v54, v57
	v_add_f32_e32 v54, 1.0, v58
	v_rcp_f32_e32 v54, v54
	v_fma_f32 v57, -v59, v59, 1.0
	v_max_f32_e32 v57, 0, v57
	v_sqrt_f32_e32 v57, v57
	v_mul_f32_e32 v198, v41, v42
	v_fma_f32 v45, v45, s100, v241
	v_exp_f32_e32 v45, v45
	v_mul_f32_e32 v42, v54, v57
	v_mul_f32_e32 v200, v42, v43
	v_fma_f32 v42, v48, s100, v211
	v_exp_f32_e32 v42, v42
	v_add_f32_e32 v43, v206, v44
	v_fma_f32 v44, v49, s100, v211
	v_add_f32_e32 v42, 1.0, v42
	v_rcp_f32_e32 v42, v42
	v_exp_f32_e32 v44, v44
	v_mul_f32_e32 v43, 0xbfb8aa3b, v43
	v_exp_f32_e32 v43, v43
	v_mul_f32_e32 v42, v243, v42
	v_add_f32_e32 v44, 1.0, v44
	v_exp_f32_e32 v42, v42
	v_rcp_f32_e32 v44, v44
	v_add_f32_e32 v43, 1.0, v43
	v_rcp_f32_e32 v43, v43
	v_fma_f32 v48, -v42, v42, 1.0
	v_mul_f32_e32 v44, v243, v44
	v_max_f32_e32 v48, 0, v48
	v_sqrt_f32_e32 v48, v48
	v_exp_f32_e32 v44, v44
	v_add_f32_e32 v45, 1.0, v45
	v_rcp_f32_e32 v45, v45
	v_mul_f32_e32 v43, v43, v48
	v_fma_f32 v48, -v44, v44, 1.0
	v_max_f32_e32 v48, 0, v48
	v_sqrt_f32_e32 v48, v48
	v_fma_f32 v40, v60, v40, v201
	v_mul_f32_e32 v52, v60, v52
	v_fma_f32 v40, v56, v40, v198
	v_mul_f32_e32 v41, v56, v52
	v_fma_f32 v40, v59, v40, v200
	v_mul_f32_e32 v41, v59, v41
	v_mul_f32_e32 v202, v43, v36
	v_fma_f32 v36, v40, v42, v202
	v_mul_f32_e32 v40, v41, v42
	v_mul_f32_e32 v41, v45, v48
	v_mul_f32_e32 v203, v41, v37
	v_fma_f32 v37, v50, s100, v211
	v_exp_f32_e32 v37, v37
	v_fma_f32 v41, v46, s100, v241
	v_exp_f32_e32 v41, v41
	v_add_f32_e32 v37, 1.0, v37
	v_rcp_f32_e32 v37, v37
	v_add_f32_e32 v41, 1.0, v41
	v_fma_f32 v46, v47, s100, v241
	v_mul_f32_e32 v37, v243, v37
	v_exp_f32_e32 v43, v37
	v_fma_f32 v37, v51, s100, v211
	v_exp_f32_e32 v37, v37
	v_fma_f32 v45, -v43, v43, 1.0
	v_max_f32_e32 v45, 0, v45
	v_rcp_f32_e32 v41, v41
	v_add_f32_e32 v37, 1.0, v37
	v_rcp_f32_e32 v37, v37
	v_sqrt_f32_e32 v45, v45
	v_exp_f32_e32 v46, v46
	v_fma_f32 v36, v44, v36, v203
	v_mul_f32_e32 v37, v243, v37
	v_exp_f32_e32 v37, v37
	v_mul_f32_e32 v41, v41, v45
	v_add_f32_e32 v45, 1.0, v46
	v_rcp_f32_e32 v45, v45
	v_fma_f32 v46, -v37, v37, 1.0
	v_max_f32_e32 v46, 0, v46
	v_sqrt_f32_e32 v46, v46
	v_mul_f32_e32 v40, v44, v40
	v_mul_f32_e32 v205, v41, v38
	v_fma_f32 v41, v43, v36, v205
	v_mul_f32_e32 v47, v43, v40
	v_mul_f32_e32 v40, v45, v46
	v_mov_b32_e32 v36, v39
	v_pk_mul_f32 v[124:125], v[40:41], v[36:37]
	s_add_i32 s82, s82, 64
	v_pk_fma_f32 v[38:39], v[40:41], v[36:37], v[124:125] op_sel:[0,0,1] op_sel_hi:[1,1,0]
	v_mul_f32_e32 v36, v37, v47
	ds_bpermute_b32 v39, v139, v36
	ds_bpermute_b32 v45, v139, v38
	ds_bpermute_b32 v48, v128, v36
	ds_bpermute_b32 v49, v128, v38
	ds_bpermute_b32 v40, v129, v36
	ds_bpermute_b32 v50, v129, v38
	s_waitcnt lgkmcnt(4)
	v_fmac_f32_e32 v45, 0, v39
	v_cndmask_b32_e64 v46, v39, 1.0, s[0:1]
	v_cndmask_b32_e64 v47, v45, 0, s[0:1]
	ds_bpermute_b32 v41, v130, v36
	s_waitcnt lgkmcnt(3)
	v_fma_f32 v36, v47, v48, v49
	v_mul_f32_e32 v51, v46, v48
	v_cndmask_b32_e64 v46, v46, v51, s[16:17]
	v_cndmask_b32_e64 v36, v47, v36, s[16:17]
	v_fmac_f32_e32 v49, v45, v48
	s_waitcnt lgkmcnt(1)
	v_fma_f32 v45, v36, v40, v50
	v_mul_f32_e32 v47, v46, v40
	v_cndmask_b32_e64 v46, v46, v47, s[4:5]
	v_cndmask_b32_e64 v36, v36, v45, s[4:5]
	v_fmac_f32_e32 v36, v210, v46
	v_fmac_f32_e32 v189, v80, v36
	v_fmac_f32_e32 v190, v81, v189
	v_fmac_f32_e32 v191, v61, v190
	v_fmac_f32_e32 v193, v78, v191
	v_fmac_f32_e32 v194, v63, v193
	v_fmac_f32_e32 v195, v72, v194
	v_fmac_f32_e32 v196, v53, v195
	v_fmac_f32_e32 v197, v68, v196
	v_fmac_f32_e32 v199, v55, v197
	v_fmac_f32_e32 v201, v60, v199
	v_fmac_f32_e32 v198, v56, v201
	v_fmac_f32_e32 v200, v59, v198
	ds_bpermute_b32 v38, v130, v38
	v_fmac_f32_e32 v202, v42, v200
	v_fmac_f32_e32 v203, v44, v202
	v_mul_f32_e32 v45, v49, v40
	v_fmac_f32_e32 v205, v43, v203
	v_fmac_f32_e32 v124, v37, v205
	v_mul_f32_e32 v36, v39, v48
	v_add_f32_e32 v37, v45, v50
	s_waitcnt lgkmcnt(1)
	v_pk_mul_f32 v[36:37], v[36:37], v[40:41]
	s_cmpk_lg_i32 s82, 0x100
	v_mul_f32_e32 v36, v36, v41
	s_waitcnt lgkmcnt(0)
	v_add_f32_e32 v46, v37, v38
	v_fmac_f32_e32 v46, v210, v36
	v_add_u32_e32 v209, 0x4400, v209
	s_cbranch_scc0 .LBB0_861
	v_mov_b32_e32 v36, v163
	v_mov_b32_e32 v37, v164
	v_mov_b32_e32 v38, v165
	v_mov_b32_e32 v39, v166
	v_mov_b32_e32 v40, v167
	v_mov_b32_e32 v41, v168
	v_mov_b32_e32 v42, v169
	v_mov_b32_e32 v43, v170
	v_mov_b32_e32 v44, v171
	v_mov_b32_e32 v45, v172
	v_mov_b32_e32 v147, v188
	v_mov_b32_e32 v148, v187
	v_mov_b32_e32 v149, v186
	v_mov_b32_e32 v150, v185
	v_mov_b32_e32 v151, v184
	v_mov_b32_e32 v152, v183
	v_mov_b32_e32 v153, v182
	v_mov_b32_e32 v154, v181
	v_mov_b32_e32 v155, v180
	v_mov_b32_e32 v156, v179
	v_mov_b32_e32 v157, v178
	v_mov_b32_e32 v158, v177
	v_mov_b32_e32 v159, v176
	v_mov_b32_e32 v160, v175
	v_mov_b32_e32 v161, v174
	v_mov_b32_e32 v162, v173
	v_mov_b32_e32 v163, v201
	v_mov_b32_e32 v164, v199
	v_mov_b32_e32 v165, v197
	v_mov_b32_e32 v166, v196
	v_mov_b32_e32 v167, v195
	v_mov_b32_e32 v168, v194
	v_mov_b32_e32 v169, v193
	v_mov_b32_e32 v170, v191
	v_mov_b32_e32 v171, v190
	v_mov_b32_e32 v172, v189
	v_mov_b32_e32 v210, v46
	s_branch .LBB0_827

; __device__ __forceinline__ float fsig(float x) { return __builtin_amdgcn_rcpf(1.0f + __expf(-x)); }
; template <bool PASS2>
; __device__ __forceinline__ void lru_item(const Frame& F, const Args& a, int item) {
;     ...
;             for (int e = 0; e < 16; ++e) { const int ee = dir ? 15 - e : e; const int rt = ee >> 2, j = ee & 3;
;                 const float rg = fsig(ar[rt][j] + ba), ig = fsig(ai[rt][j] + bi); const float la = logu * rg; const float av = __expf(la);
;                 const float mult = (t0 + tl0 + ee == tstart) ? 1.0f : __builtin_amdgcn_sqrtf(fmaxf(1.0f - av * av, 0.f)); const float bv = mult * ig * ax[rt][j];
;                 ar[rt][j] = av; ai[rt][j] = bv; B16 = av * B16 + bv; A16 = av * A16; }
.LBB0_864:
	s_nop 3
	v_fma_f32 v83, v83, s100, v211
	v_exp_f32_e32 v83, v83
	v_fma_f32 v79, v79, s100, v241
	v_exp_f32_e32 v79, v79
	v_add_f32_e32 v83, 1.0, v83
	v_rcp_f32_e32 v83, v83
	s_xor_b32 s29, s46, 0xc0
	v_add_f32_e32 v79, 1.0, v79
	v_mul_f32_e32 v83, v243, v83
	v_exp_f32_e32 v83, v83
	v_or_b32_e32 v84, s29, v103
	v_fma_f32 v82, v82, s100, v211
	v_rcp_f32_e32 v79, v79
	v_fma_f32 v86, -v83, v83, 1.0
	v_max_f32_e32 v86, 0, v86
	v_sqrt_f32_e32 v86, v86
	v_add_u32_e32 v85, s79, v84
	v_exp_f32_e32 v82, v82
	v_cmp_ne_u32_e32 vcc, s76, v85
	v_fma_f32 v81, v81, s100, v211
	v_cndmask_b32_e32 v85, 1.0, v86, vcc
	v_mul_f32_e32 v79, v79, v85
	v_mul_f32_e32 v75, v79, v75
	v_add_f32_e32 v79, 1.0, v82
	v_rcp_f32_e32 v79, v79
	v_exp_f32_e32 v81, v81
	v_fma_f32 v78, v78, s100, v241
	v_mul_f32_e32 v79, v243, v79
	v_add_f32_e32 v81, 1.0, v81
	v_exp_f32_e32 v79, v79
	v_rcp_f32_e32 v81, v81
	v_exp_f32_e32 v78, v78
	v_fma_f32 v85, -v79, v79, 1.0
	v_mul_f32_e32 v81, v243, v81
	v_add_f32_e32 v78, 1.0, v78
	v_max_f32_e32 v85, 0, v85
	v_rcp_f32_e32 v78, v78
	v_sqrt_f32_e32 v85, v85
	v_fma_f32 v77, v77, s100, v241
	v_exp_f32_e32 v81, v81
	v_exp_f32_e32 v77, v77
	v_mul_f32_e32 v78, v78, v85
	v_fma_f32 v82, 0, v83, v75
	v_fma_f32 v85, -v81, v81, 1.0
	v_add_f32_e32 v77, 1.0, v77
	v_max_f32_e32 v85, 0, v85
	v_rcp_f32_e32 v77, v77
	v_sqrt_f32_e32 v85, v85
	v_mul_f32_e32 v74, v78, v74
	v_fma_f32 v78, v79, v82, v74
	v_mul_f32_e32 v77, v77, v85
	v_mul_f32_e32 v73, v77, v73
	v_fma_f32 v77, v81, v78, v73
	v_fma_f32 v78, v80, s100, v211
	v_exp_f32_e32 v78, v78
	v_fma_f32 v71, v71, s100, v211
	v_exp_f32_e32 v71, v71
	v_add_f32_e32 v78, 1.0, v78
	v_rcp_f32_e32 v78, v78
	v_add_f32_e32 v71, 1.0, v71
	v_fma_f32 v76, v76, s100, v241
	v_rcp_f32_e32 v71, v71
	v_mul_f32_e32 v78, v243, v78
	v_exp_f32_e32 v78, v78
	v_exp_f32_e32 v76, v76
	v_fma_f32 v70, v70, s100, v211
	v_mul_f32_e32 v82, v83, v79
	v_exp_f32_e32 v70, v70
	v_mul_f32_e32 v80, v81, v82
	v_fma_f32 v82, -v78, v78, 1.0
	v_mul_f32_e32 v71, v243, v71
	v_add_f32_e32 v76, 1.0, v76
	v_max_f32_e32 v82, 0, v82
	v_rcp_f32_e32 v76, v76
	v_sqrt_f32_e32 v82, v82
	v_fma_f32 v67, v67, s100, v241
	v_exp_f32_e32 v71, v71
	v_exp_f32_e32 v67, v67
	v_add_f32_e32 v70, 1.0, v70
	v_rcp_f32_e32 v70, v70
	v_fma_f32 v69, v69, s100, v211
	v_exp_f32_e32 v69, v69
	v_mul_f32_e32 v76, v76, v82
	v_fma_f32 v82, -v71, v71, 1.0
	v_add_f32_e32 v67, 1.0, v67
	v_max_f32_e32 v82, 0, v82
	v_rcp_f32_e32 v67, v67
	v_sqrt_f32_e32 v82, v82
	v_mul_f32_e32 v70, v243, v70
	v_add_f32_e32 v69, 1.0, v69
	v_fma_f32 v66, v66, s100, v241
	v_exp_f32_e32 v70, v70
	v_rcp_f32_e32 v69, v69
	v_exp_f32_e32 v66, v66
	v_mul_f32_e32 v72, v76, v72
	v_mul_f32_e32 v67, v67, v82
	v_fma_f32 v76, v78, v77, v72
	v_mul_f32_e32 v77, v78, v80
	v_mul_f32_e32 v63, v67, v63
	v_fma_f32 v67, v71, v76, v63
	v_mul_f32_e32 v76, v71, v77
	v_fma_f32 v77, -v70, v70, 1.0
	v_mul_f32_e32 v69, v243, v69
	v_add_f32_e32 v66, 1.0, v66
	v_max_f32_e32 v77, 0, v77
	v_rcp_f32_e32 v66, v66
	v_sqrt_f32_e32 v77, v77
	v_fma_f32 v65, v65, s100, v241
	v_exp_f32_e32 v69, v69
	v_exp_f32_e32 v65, v65
	v_mul_f32_e32 v66, v66, v77
	v_mul_f32_e32 v62, v66, v62
	v_fma_f32 v77, -v69, v69, 1.0
	v_add_f32_e32 v65, 1.0, v65
	v_max_f32_e32 v77, 0, v77
	v_rcp_f32_e32 v65, v65
	v_sqrt_f32_e32 v77, v77
	v_fma_f32 v66, v70, v67, v62
	v_fma_f32 v59, v59, s100, v211
	v_mul_f32_e32 v65, v65, v77
	v_mul_f32_e32 v61, v65, v61
	v_fma_f32 v65, v69, v66, v61
	v_fma_f32 v66, v68, s100, v211
	v_exp_f32_e32 v66, v66
	v_exp_f32_e32 v59, v59
	v_fma_f32 v64, v64, s100, v241
	v_add_f32_e32 v66, 1.0, v66
	v_rcp_f32_e32 v66, v66
	v_add_f32_e32 v59, 1.0, v59
	v_rcp_f32_e32 v59, v59
	v_exp_f32_e32 v64, v64
	v_mul_f32_e32 v66, v243, v66
	v_exp_f32_e32 v66, v66
	v_mul_f32_e32 v59, v243, v59
	v_add_f32_e32 v64, 1.0, v64
	v_fma_f32 v68, -v66, v66, 1.0
	v_max_f32_e32 v68, 0, v68
	v_rcp_f32_e32 v64, v64
	v_sqrt_f32_e32 v68, v68
	v_fma_f32 v55, v55, s100, v241
	v_exp_f32_e32 v59, v59
	v_exp_f32_e32 v55, v55
	v_mul_f32_e32 v64, v64, v68
	v_mul_f32_e32 v67, v70, v76
	v_fma_f32 v68, -v59, v59, 1.0
	v_add_f32_e32 v55, 1.0, v55
	v_max_f32_e32 v68, 0, v68
	v_rcp_f32_e32 v55, v55
	v_sqrt_f32_e32 v68, v68
	v_mul_f32_e32 v67, v69, v67
	v_mul_f32_e32 v60, v64, v60
	v_fma_f32 v64, v66, v65, v60
	v_mul_f32_e32 v55, v55, v68
	v_mul_f32_e32 v65, v66, v67
	v_mul_f32_e32 v67, v55, v51
	v_fma_f32 v55, v58, s100, v211
	v_exp_f32_e32 v55, v55
	v_fma_f32 v51, v59, v64, v67
	v_fma_f32 v54, v54, s100, v241
	v_add_f32_e32 v55, 1.0, v55
	v_rcp_f32_e32 v55, v55
	v_exp_f32_e32 v54, v54
	v_mul_f32_e32 v58, v59, v65
	v_mul_f32_e32 v55, v243, v55
	v_exp_f32_e32 v64, v55
	v_fma_f32 v55, v57, s100, v211
	v_exp_f32_e32 v55, v55
	v_fma_f32 v53, v53, s100, v241
	v_exp_f32_e32 v53, v53
	v_fma_f32 v57, -v64, v64, 1.0
	v_add_f32_e32 v55, 1.0, v55
	v_rcp_f32_e32 v55, v55
	v_add_f32_e32 v54, 1.0, v54
	v_max_f32_e32 v57, 0, v57
	v_rcp_f32_e32 v54, v54
	v_mul_f32_e32 v55, v243, v55
	v_exp_f32_e32 v65, v55
	v_sqrt_f32_e32 v57, v57
	v_add_f32_e32 v53, 1.0, v53
	v_rcp_f32_e32 v53, v53
	v_fma_f32 v55, -v65, v65, 1.0
	v_max_f32_e32 v55, 0, v55
	v_sqrt_f32_e32 v55, v55
	v_mul_f32_e32 v54, v54, v57
	v_mul_f32_e32 v57, v54, v50
	v_fma_f32 v50, v64, v51, v57
	v_mul_f32_e32 v53, v53, v55
	v_mul_f32_e32 v51, v64, v58
	v_mul_f32_e32 v58, v53, v49
	v_fma_f32 v49, v65, v50, v58
	v_fma_f32 v50, v56, s100, v211
	v_exp_f32_e32 v50, v50
	v_fma_f32 v47, v47, s100, v211
	v_exp_f32_e32 v47, v47
	v_add_f32_e32 v50, 1.0, v50
	v_rcp_f32_e32 v50, v50
	v_add_f32_e32 v47, 1.0, v47
	v_fma_f32 v52, v52, s100, v241
	v_mul_f32_e32 v50, v243, v50
	v_exp_f32_e32 v56, v50
	v_rcp_f32_e32 v47, v47
	v_exp_f32_e32 v52, v52
; #define LAS __attribute__((address_space(3)))
; __device__ __forceinline__ unsigned cvt_pk_bf16(float lo, float hi) { unsigned r; asm volatile("v_cvt_pk_bf16_f32 %0, %1, %2" : "=v"(r) : "v"(lo), "v"(hi)); return r; }
; __device__ __forceinline__ float bf2f(unsigned short b) { return __uint_as_float(((unsigned)b) << 16); }
; __device__ __forceinline__ float fsig(float x) { return __builtin_amdgcn_rcpf(1.0f + __expf(-x)); }
; template <bool PASS2>
; __device__ __forceinline__ void lru_item(const Frame& F, const Args& a, int item) {
;     ...
;             for (int e = 0; e < 16; ++e) { const int ee = dir ? 15 - e : e; const int rt = ee >> 2, j = ee & 3;
;                 const float rg = fsig(ar[rt][j] + ba), ig = fsig(ai[rt][j] + bi); const float la = logu * rg; const float av = __expf(la);
;                 const float mult = (t0 + tl0 + ee == tstart) ? 1.0f : __builtin_amdgcn_sqrtf(fmaxf(1.0f - av * av, 0.f)); const float bv = mult * ig * ax[rt][j];
;                 ar[rt][j] = av; ai[rt][j] = bv; B16 = av * B16 + bv; A16 = av * A16; }
;             const int pos = dir ? 3 - fq : fq;
;             float PA = 1.f, PB = 0.f, QA = 1.f, QB = 0.f;
; #pragma unroll
;             for (int i = 0; i < 4; ++i) { const int k = dir ? 3 - i : i; const float Ak = __shfl(A16, fr + 16 * k), Bk = __shfl(B16, fr + 16 * k);
;                 if (i < pos) { PB = Ak * PB + Bk; PA = Ak * PA; }
;                 QB = Ak * QB + Bk; QA = Ak * QA; }
;             if (PASS2) {
;                 float h = PA * hc + PB;
; #pragma unroll
;                 for (int e = 0; e < 16; ++e) { const int ee = dir ? 15 - e : e; const int rt = ee >> 2, j = ee & 3; h = ar[rt][j] * h + ai[rt][j];
;                     if (dir == 0) hf[3][rt][j] = h;
;                     else { LAS unsigned short* yp = (LAS unsigned short*)(R0 + (tl0 + ee) * AT_PITCH + 2 * c); const float yb = bf2f(*yp);
;                         const float u2 = 1.5957691216057308f * (yb + 0.044715f * yb * yb * yb);
;                         const float y = (hf[3][rt][j] + h) * yb * fsig(u2);
;                         *yp = (unsigned short)(cvt_pk_bf16(y, 0.f) & 0xffffu); } }
	v_mul_f32_e32 v53, v65, v51
	v_fma_f32 v50, -v56, v56, 1.0
	v_mul_f32_e32 v47, v243, v47
	v_add_f32_e32 v51, 1.0, v52
	v_max_f32_e32 v50, 0, v50
	v_rcp_f32_e32 v51, v51
	v_sqrt_f32_e32 v50, v50
	v_fma_f32 v43, v43, s100, v241
	v_exp_f32_e32 v47, v47
	v_exp_f32_e32 v43, v43
	v_mul_f32_e32 v50, v51, v50
	v_mul_f32_e32 v68, v50, v48
	v_fma_f32 v51, -v47, v47, 1.0
	v_add_f32_e32 v43, 1.0, v43
	v_max_f32_e32 v51, 0, v51
	v_rcp_f32_e32 v43, v43
	v_sqrt_f32_e32 v52, v51
	v_fma_f32 v42, v42, s100, v241
	v_exp_f32_e32 v42, v42
	v_mul_f32_e32 v50, v43, v52
	v_fma_f32 v43, v46, s100, v211
	v_exp_f32_e32 v43, v43
	v_mov_b32_e32 v46, v39
	v_add_f32_e32 v42, 1.0, v42
	v_rcp_f32_e32 v42, v42
	v_add_f32_e32 v39, 1.0, v43
	v_rcp_f32_e32 v39, v39
	v_fma_f32 v51, v56, v49, v68
	v_fma_f32 v45, v45, s100, v211
	v_mul_f32_e32 v39, v243, v39
	v_exp_f32_e32 v39, v39
	v_pk_mul_f32 v[48:49], v[50:51], v[46:47]
	v_exp_f32_e32 v45, v45
	v_pk_fma_f32 v[50:51], v[50:51], v[46:47], v[48:49] op_sel_hi:[1,1,0]
	v_fma_f32 v43, -v39, v39, 1.0
	v_max_f32_e32 v43, 0, v43
	v_sqrt_f32_e32 v43, v43
	v_mul_f32_e32 v53, v56, v53
	v_mul_f32_e32 v46, v47, v53
	v_mul_f32_e32 v50, v42, v43
	v_pk_mul_f32 v[42:43], v[50:51], v[38:39]
	v_fma_f32 v44, v44, s100, v211
	v_pk_fma_f32 v[50:51], v[50:51], v[38:39], v[42:43] op_sel_hi:[1,1,0]
	v_add_f32_e32 v38, 1.0, v45
	v_rcp_f32_e32 v38, v38
	v_fma_f32 v41, v41, s100, v241
	v_exp_f32_e32 v41, v41
	v_mul_f32_e32 v38, v243, v38
	v_exp_f32_e32 v45, v38
	v_mul_f32_e32 v38, v39, v46
	v_exp_f32_e32 v46, v44
	v_mov_b32_e32 v44, v37
	v_fma_f32 v43, -v45, v45, 1.0
	v_add_f32_e32 v37, 1.0, v46
	v_rcp_f32_e32 v37, v37
	v_fma_f32 v40, v40, s100, v241
	v_add_f32_e32 v41, 1.0, v41
	v_max_f32_e32 v43, 0, v43
	v_mul_f32_e32 v37, v243, v37
	v_exp_f32_e32 v40, v40
	v_rcp_f32_e32 v41, v41
	v_sqrt_f32_e32 v43, v43
	v_exp_f32_e32 v37, v37
	v_add_f32_e32 v40, 1.0, v40
	v_mul_f32_e32 v38, v45, v38
	v_mul_f32_e32 v50, v41, v43
	v_rcp_f32_e32 v43, v40
	v_fma_f32 v40, -v37, v37, 1.0
	v_max_f32_e32 v40, 0, v40
	v_sqrt_f32_e32 v46, v40
	v_pk_mul_f32 v[40:41], v[50:51], v[44:45]
	s_add_i32 s46, s46, 64
	v_pk_fma_f32 v[52:53], v[50:51], v[44:45], v[40:41] op_sel_hi:[1,1,0]
	s_cmpk_lg_i32 s46, 0x100
	v_mul_f32_e32 v52, v43, v46
	v_pk_mul_f32 v[50:51], v[52:53], v[36:37]
	s_nop 0
	v_pk_fma_f32 v[54:55], v[52:53], v[36:37], v[50:51] op_sel:[0,0,1] op_sel_hi:[1,1,0]
	v_mad_u64_u32 v[52:53], s[30:31], v84, s33, v[120:121]
	v_mul_f32_e32 v36, v37, v38
	ds_read_u16 v38, v52 offset:4080
	ds_bpermute_b32 v41, v130, v36
	ds_bpermute_b32 v43, v130, v54
	ds_bpermute_b32 v49, v129, v36
	ds_bpermute_b32 v55, v129, v54
	s_waitcnt lgkmcnt(4)
	v_lshlrev_b32_e32 v51, 16, v38
	v_mul_f32_e32 v38, 0x3d372713, v51
	v_mul_f32_e32 v38, v38, v51
	v_fma_f32 v38, v38, v51, v51
	v_mul_f32_e32 v38, 0xc0135761, v38
	v_exp_f32_e32 v53, v38
	ds_bpermute_b32 v38, v128, v36
	ds_bpermute_b32 v76, v128, v54
	s_waitcnt lgkmcnt(4)
	v_fmac_f32_e32 v43, 0, v41
	v_cndmask_b32_e64 v44, v41, 1.0, s[4:5]
	v_cndmask_b32_e64 v46, v43, 0, s[4:5]
	s_waitcnt lgkmcnt(2)
	v_fma_f32 v77, v46, v49, v55
	v_mul_f32_e32 v80, v44, v49
	v_cndmask_b32_e64 v44, v44, v80, s[6:7]
	v_cndmask_b32_e64 v46, v46, v77, s[6:7]
	s_waitcnt lgkmcnt(0)
	v_fma_f32 v77, v46, v38, v76
	v_mul_f32_e32 v80, v44, v38
	v_add_f32_e32 v53, 1.0, v53
	v_cndmask_b32_e64 v44, v44, v80, s[0:1]
	v_cndmask_b32_e64 v46, v46, v77, s[0:1]
	v_rcp_f32_e32 v53, v53
	v_fmac_f32_e32 v46, v127, v44
	v_fmac_f32_e32 v75, v83, v46
	v_add_f32_e32 v44, v124, v75
	v_mul_f32_e32 v44, v44, v51
	v_mul_f32_e32 v44, v44, v53
	v_cvt_pk_bf16_f32 v44, v44, v97
	ds_read_u16 v46, v52 offset:3808
	ds_write_b16 v52, v44 offset:4080
	v_fmac_f32_e32 v74, v79, v75
	v_fmac_f32_e32 v73, v81, v74
	v_fmac_f32_e32 v72, v78, v73
	s_waitcnt lgkmcnt(1)
	v_lshlrev_b32_e32 v46, 16, v46
	v_mul_f32_e32 v51, 0x3d372713, v46
	v_mul_f32_e32 v51, v51, v46
	v_fma_f32 v51, v51, v46, v46
	v_mul_f32_e32 v51, 0xc0135761, v51
	v_exp_f32_e32 v51, v51
	v_fmac_f32_e32 v63, v71, v72
	v_fmac_f32_e32 v62, v70, v63
	v_fmac_f32_e32 v61, v69, v62
	v_add_f32_e32 v44, 1.0, v51
	v_rcp_f32_e32 v44, v44
	v_add_f32_e32 v51, v205, v74
	v_mul_f32_e32 v46, v51, v46
	v_fmac_f32_e32 v60, v66, v61
	v_mul_f32_e32 v44, v46, v44
	v_cvt_pk_bf16_f32 v44, v44, v97
	ds_read_u16 v46, v52 offset:3536
	ds_write_b16 v52, v44 offset:3808
	v_fmac_f32_e32 v67, v59, v60
	v_fmac_f32_e32 v57, v64, v67
	v_fmac_f32_e32 v58, v65, v57
	s_waitcnt lgkmcnt(1)
	v_lshlrev_b32_e32 v46, 16, v46
	v_mul_f32_e32 v51, 0x3d372713, v46
	v_mul_f32_e32 v51, v51, v46
	v_fma_f32 v51, v51, v46, v46
	v_mul_f32_e32 v51, 0xc0135761, v51
	v_exp_f32_e32 v51, v51
	v_fmac_f32_e32 v68, v56, v58
	v_fmac_f32_e32 v48, v47, v68
	v_add_f32_e32 v47, v193, v48
	v_add_f32_e32 v44, 1.0, v51
	v_rcp_f32_e32 v44, v44
	v_add_f32_e32 v51, v203, v73
	v_mul_f32_e32 v46, v51, v46
	v_fmac_f32_e32 v42, v39, v48
	v_mul_f32_e32 v44, v46, v44
	v_cvt_pk_bf16_f32 v44, v44, v97
	ds_read_u16 v46, v52 offset:3264
	ds_write_b16 v52, v44 offset:3536
	v_add_f32_e32 v39, v191, v42
	v_fmac_f32_e32 v40, v45, v42
	v_add_f32_e32 v42, v190, v40
	s_waitcnt lgkmcnt(1)
	v_lshlrev_b32_e32 v46, 16, v46
	v_mul_f32_e32 v51, 0x3d372713, v46
	v_mul_f32_e32 v51, v51, v46
	v_fma_f32 v51, v51, v46, v46
	v_mul_f32_e32 v51, 0xc0135761, v51
	v_exp_f32_e32 v51, v51
	v_fmac_f32_e32 v50, v37, v40
	v_add_f32_e32 v37, v189, v50
	ds_bpermute_b32 v45, v139, v54
	v_add_f32_e32 v44, 1.0, v51
	v_rcp_f32_e32 v44, v44
	v_add_f32_e32 v51, v202, v72
	v_mul_f32_e32 v46, v51, v46
	v_fmac_f32_e32 v55, v43, v49
	v_mul_f32_e32 v44, v46, v44
	v_cvt_pk_bf16_f32 v44, v44, v97
	ds_read_u16 v46, v52 offset:2992
	ds_write_b16 v52, v44 offset:3264
	v_mul_f32_e32 v43, v55, v38
	v_mov_b32_e32 v124, v133
	v_mov_b32_e32 v205, v142
	s_waitcnt lgkmcnt(1)
; #define LAS __attribute__((address_space(3)))
; __device__ __forceinline__ unsigned cvt_pk_bf16(float lo, float hi) { unsigned r; asm volatile("v_cvt_pk_bf16_f32 %0, %1, %2" : "=v"(r) : "v"(lo), "v"(hi)); return r; }
; __device__ __forceinline__ float bf2f(unsigned short b) { return __uint_as_float(((unsigned)b) << 16); }
; __device__ __forceinline__ float fsig(float x) { return __builtin_amdgcn_rcpf(1.0f + __expf(-x)); }
; template <bool PASS2>
; __device__ __forceinline__ void lru_item(const Frame& F, const Args& a, int item) {
;     ...
;                 float h = PA * hc + PB;
; #pragma unroll
;                 for (int e = 0; e < 16; ++e) { const int ee = dir ? 15 - e : e; const int rt = ee >> 2, j = ee & 3; h = ar[rt][j] * h + ai[rt][j];
;                     if (dir == 0) hf[3][rt][j] = h;
;                     else { LAS unsigned short* yp = (LAS unsigned short*)(R0 + (tl0 + ee) * AT_PITCH + 2 * c); const float yb = bf2f(*yp);
;                         const float u2 = 1.5957691216057308f * (yb + 0.044715f * yb * yb * yb);
;                         const float y = (hf[3][rt][j] + h) * yb * fsig(u2);
;                         *yp = (unsigned short)(cvt_pk_bf16(y, 0.f) & 0xffffu); } }
;                 hc = QA * hc + QB;
	v_lshlrev_b32_e32 v46, 16, v46
	v_mul_f32_e32 v51, 0x3d372713, v46
	v_mul_f32_e32 v51, v51, v46
	v_fma_f32 v51, v51, v46, v46
	v_mul_f32_e32 v51, 0xc0135761, v51
	v_exp_f32_e32 v51, v51
	v_mov_b32_e32 v203, v143
	v_mov_b32_e32 v202, v146
	v_mov_b32_e32 v193, v169
	v_add_f32_e32 v44, 1.0, v51
	v_rcp_f32_e32 v44, v44
	v_add_f32_e32 v51, v200, v63
	v_mul_f32_e32 v46, v51, v46
	v_mov_b32_e32 v200, v131
	v_mul_f32_e32 v44, v46, v44
	v_cvt_pk_bf16_f32 v44, v44, v97
	ds_read_u16 v46, v52 offset:2720
	ds_write_b16 v52, v44 offset:2992
	v_mov_b32_e32 v191, v170
	v_mov_b32_e32 v190, v171
	v_mov_b32_e32 v189, v172
	s_waitcnt lgkmcnt(1)
	v_lshlrev_b32_e32 v46, 16, v46
	v_mul_f32_e32 v51, 0x3d372713, v46
	v_mul_f32_e32 v51, v51, v46
	v_fma_f32 v51, v51, v46, v46
	v_mul_f32_e32 v51, 0xc0135761, v51
	v_exp_f32_e32 v51, v51
	v_mov_b32_e32 v133, v188
	v_mov_b32_e32 v142, v187
	v_mov_b32_e32 v143, v186
	v_add_f32_e32 v44, 1.0, v51
	v_rcp_f32_e32 v44, v44
	v_add_f32_e32 v51, v198, v62
	v_mul_f32_e32 v46, v51, v46
	v_mov_b32_e32 v198, v132
	v_mul_f32_e32 v44, v46, v44
	v_cvt_pk_bf16_f32 v44, v44, v97
	ds_read_u16 v46, v52 offset:2448
	ds_write_b16 v52, v44 offset:2720
	v_mov_b32_e32 v146, v185
	v_mov_b32_e32 v131, v184
	v_mov_b32_e32 v132, v183
	s_waitcnt lgkmcnt(1)
	v_lshlrev_b32_e32 v46, 16, v46
	v_mul_f32_e32 v51, 0x3d372713, v46
	v_mul_f32_e32 v51, v51, v46
	v_fma_f32 v51, v51, v46, v46
	v_mul_f32_e32 v51, 0xc0135761, v51
	v_exp_f32_e32 v51, v51
	v_mov_b32_e32 v169, v176
	v_mov_b32_e32 v170, v175
	v_mov_b32_e32 v171, v174
	v_add_f32_e32 v44, 1.0, v51
	v_rcp_f32_e32 v44, v44
	v_add_f32_e32 v51, v201, v61
	v_mul_f32_e32 v46, v51, v46
	v_mov_b32_e32 v201, v163
	v_mul_f32_e32 v44, v46, v44
	v_cvt_pk_bf16_f32 v44, v44, v97
	ds_read_u16 v46, v52 offset:2176
	ds_write_b16 v52, v44 offset:2448
	v_mov_b32_e32 v163, v182
	v_mov_b32_e32 v172, v173
	v_mov_b32_e32 v188, v147
	s_waitcnt lgkmcnt(1)
	v_lshlrev_b32_e32 v46, 16, v46
	v_mul_f32_e32 v51, 0x3d372713, v46
	v_mul_f32_e32 v51, v51, v46
	v_fma_f32 v51, v51, v46, v46
	v_mul_f32_e32 v51, 0xc0135761, v51
	v_exp_f32_e32 v51, v51
	v_mov_b32_e32 v187, v148
	v_mov_b32_e32 v186, v149
	v_mov_b32_e32 v185, v150
	v_add_f32_e32 v44, 1.0, v51
	v_rcp_f32_e32 v44, v44
	v_add_f32_e32 v51, v199, v60
	v_mul_f32_e32 v46, v51, v46
	v_mov_b32_e32 v199, v164
	v_mul_f32_e32 v44, v46, v44
	v_cvt_pk_bf16_f32 v44, v44, v97
	ds_read_u16 v46, v52 offset:1904
	ds_write_b16 v52, v44 offset:2176
	v_mov_b32_e32 v164, v181
	v_mov_b32_e32 v184, v151
	v_mov_b32_e32 v183, v152
	s_waitcnt lgkmcnt(1)
	v_lshlrev_b32_e32 v46, 16, v46
	v_mul_f32_e32 v51, 0x3d372713, v46
	v_mul_f32_e32 v51, v51, v46
	v_fma_f32 v51, v51, v46, v46
	v_mul_f32_e32 v51, 0xc0135761, v51
	v_exp_f32_e32 v51, v51
	v_mov_b32_e32 v182, v153
	v_mov_b32_e32 v181, v154
	v_mov_b32_e32 v176, v159
	v_add_f32_e32 v44, 1.0, v51
	v_rcp_f32_e32 v44, v44
	v_add_f32_e32 v51, v197, v67
	v_mul_f32_e32 v46, v51, v46
	v_mov_b32_e32 v197, v165
	v_mul_f32_e32 v44, v46, v44
	v_cvt_pk_bf16_f32 v44, v44, v97
	ds_read_u16 v46, v52 offset:1632
	ds_write_b16 v52, v44 offset:1904
	v_mov_b32_e32 v165, v180
	v_mov_b32_e32 v180, v155
	v_mov_b32_e32 v175, v160
	s_waitcnt lgkmcnt(1)
	v_lshlrev_b32_e32 v46, 16, v46
	v_mul_f32_e32 v51, 0x3d372713, v46
	v_mul_f32_e32 v51, v51, v46
	v_fma_f32 v51, v51, v46, v46
	v_mul_f32_e32 v51, 0xc0135761, v51
	v_exp_f32_e32 v51, v51
	v_mov_b32_e32 v174, v161
	v_mov_b32_e32 v173, v162
	v_add_f32_e32 v44, 1.0, v51
	v_rcp_f32_e32 v44, v44
	v_add_f32_e32 v51, v196, v57
	v_mul_f32_e32 v46, v51, v46
	v_mov_b32_e32 v196, v166
	v_mul_f32_e32 v44, v46, v44
	v_cvt_pk_bf16_f32 v44, v44, v97
	ds_read_u16 v46, v52 offset:1360
	ds_write_b16 v52, v44 offset:1632
	v_mov_b32_e32 v166, v179
	v_mov_b32_e32 v179, v156
	s_waitcnt lgkmcnt(1)
	v_lshlrev_b32_e32 v46, 16, v46
	v_mul_f32_e32 v51, 0x3d372713, v46
	v_mul_f32_e32 v51, v51, v46
	v_fma_f32 v51, v51, v46, v46
	v_mul_f32_e32 v51, 0xc0135761, v51
	v_exp_f32_e32 v51, v51
	s_nop 0
	v_add_f32_e32 v44, 1.0, v51
	v_rcp_f32_e32 v44, v44
	v_add_f32_e32 v51, v195, v58
	v_mul_f32_e32 v46, v51, v46
	v_mov_b32_e32 v195, v167
	v_mul_f32_e32 v44, v46, v44
	v_cvt_pk_bf16_f32 v44, v44, v97
	ds_read_u16 v46, v52 offset:1088
	ds_write_b16 v52, v44 offset:1360
	v_mov_b32_e32 v167, v178
	v_mov_b32_e32 v178, v157
	s_waitcnt lgkmcnt(1)
	v_lshlrev_b32_e32 v46, 16, v46
	v_mul_f32_e32 v51, 0x3d372713, v46
	v_mul_f32_e32 v51, v51, v46
	v_fma_f32 v51, v51, v46, v46
	v_mul_f32_e32 v51, 0xc0135761, v51
	v_exp_f32_e32 v51, v51
	s_nop 0
	v_add_f32_e32 v44, 1.0, v51
	v_rcp_f32_e32 v44, v44
	v_add_f32_e32 v51, v194, v68
	v_mul_f32_e32 v46, v51, v46
	v_mov_b32_e32 v194, v168
	v_mul_f32_e32 v44, v46, v44
	v_cvt_pk_bf16_f32 v44, v44, v97
	ds_read_u16 v46, v52 offset:816
	ds_write_b16 v52, v44 offset:1088
	v_mov_b32_e32 v168, v177
	v_mov_b32_e32 v177, v158
	s_waitcnt lgkmcnt(1)
	v_lshlrev_b32_e32 v46, 16, v46
	v_mul_f32_e32 v51, 0x3d372713, v46
	v_mul_f32_e32 v51, v51, v46
	v_fma_f32 v51, v51, v46, v46
	v_mul_f32_e32 v51, 0xc0135761, v51
	v_exp_f32_e32 v51, v51
	v_mul_f32_e32 v46, v47, v46
	v_add_f32_e32 v44, 1.0, v51
	v_rcp_f32_e32 v44, v44
	s_nop 0
	v_mul_f32_e32 v44, v46, v44
	v_cvt_pk_bf16_f32 v44, v44, v97
	ds_read_u16 v46, v52 offset:544
	ds_write_b16 v52, v44 offset:816
	s_waitcnt lgkmcnt(1)
	v_lshlrev_b32_e32 v46, 16, v46
	v_mul_f32_e32 v47, 0x3d372713, v46
	v_mul_f32_e32 v47, v47, v46
	v_fma_f32 v47, v47, v46, v46
	v_mul_f32_e32 v47, 0xc0135761, v47
	v_exp_f32_e32 v47, v47
	v_mul_f32_e32 v39, v39, v46
	v_add_f32_e32 v44, 1.0, v47
	v_rcp_f32_e32 v44, v44
	s_nop 0
	v_mul_f32_e32 v39, v39, v44
	v_cvt_pk_bf16_f32 v39, v39, v97
	ds_read_u16 v44, v52 offset:272
	ds_write_b16 v52, v39 offset:544
	s_waitcnt lgkmcnt(1)
	v_lshlrev_b32_e32 v44, 16, v44
	v_mul_f32_e32 v46, 0x3d372713, v44
	v_mul_f32_e32 v46, v46, v44
	v_fma_f32 v46, v46, v44, v44
	v_mul_f32_e32 v46, 0xc0135761, v46
	v_exp_f32_e32 v46, v46
	v_mul_f32_e32 v42, v42, v44
	v_add_f32_e32 v39, 1.0, v46
	v_rcp_f32_e32 v39, v39
	s_nop 0
	v_mul_f32_e32 v39, v42, v39
	v_cvt_pk_bf16_f32 v42, v39, v97
	ds_read_u16 v44, v52
	ds_bpermute_b32 v39, v139, v36
	ds_write_b16 v52, v42 offset:272
	s_waitcnt lgkmcnt(2)
	v_lshlrev_b32_e32 v36, 16, v44
	v_mul_f32_e32 v44, 0x3d372713, v36
	v_mul_f32_e32 v44, v44, v36
	v_fma_f32 v44, v44, v36, v36
	v_mul_f32_e32 v44, 0xc0135761, v44
	v_exp_f32_e32 v44, v44
	v_mul_f32_e32 v36, v37, v36
	v_add_f32_e32 v37, v43, v76
	v_add_f32_e32 v42, 1.0, v44
	v_rcp_f32_e32 v42, v42
	s_nop 0
	v_mul_f32_e32 v36, v36, v42
	v_cvt_pk_bf16_f32 v36, v36, v97
	ds_write_b16 v52, v36
	v_mul_f32_e32 v36, v41, v49
	s_waitcnt lgkmcnt(2)
	v_pk_mul_f32 v[36:37], v[36:37], v[38:39]
	s_nop 0
	v_mul_f32_e32 v36, v36, v39
	v_add_f32_e32 v37, v37, v45
	v_fmac_f32_e32 v37, v127, v36
	v_mov_b32_e32 v127, v37
	s_cbranch_scc0 .LBB0_817
; #define LAS __attribute__((address_space(3)))
; template <bool PASS2>
; __device__ __forceinline__ void lru_item(const Frame& F, const Args& a, int item) {
;     ...
;         for (int si = 0; si < 4; ++si) { const int s = dir ? 3 - si : si;
;             if (PASS2 && dir == 0) {
; #pragma unroll
;                 for (int i1 = 0; i1 < 4; ++i1)
; #pragma unroll
;                     for (int i2 = 0; i2 < 4; ++i2) { hf[0][i1][i2] = hf[1][i1][i2]; hf[1][i1][i2] = hf[2][i1][i2]; hf[2][i1][i2] = hf[3][i1][i2]; } }
;             f32x4 ar[4], ai[4], ax[4];
; #pragma unroll
;             for (int rt = 0; rt < 4; ++rt) { ar[rt] = (f32x4){0.f, 0.f, 0.f, 0.f}; ai[rt] = (f32x4){0.f, 0.f, 0.f, 0.f}; ax[rt] = (f32x4){0.f, 0.f, 0.f, 0.f};
; #pragma unroll
;                 for (int ks = 0; ks < 4; ++ks) { const bf16x8 xf = *(const LAS bf16x8*)(AT + (64 * s + 16 * rt + fr) * AT_PITCH + 64 * ks + 16 * fq);
;                     ar[rt] = __builtin_amdgcn_mfma_f32_16x16x32_bf16(xf, wrf[ks], ar[rt], 0, 0, 0); ai[rt] = __builtin_amdgcn_mfma_f32_16x16x32_bf16(xf, wif[ks], ai[rt], 0, 0, 0);
;                     if (ks == ks0) ax[rt] = __builtin_amdgcn_mfma_f32_16x16x32_bf16(xf, sel, ax[rt], 0, 0, 0); } }
.LBB0_865:
	v_mul_f32_e32 v243, 0x3fb8aa3b, v126
	s_mov_b32 s100, 0xbfb8aa3b
	v_mul_f32_e32 v211, 0xbfb8aa3b, v125
	v_mul_f32_e32 v241, 0xbfb8aa3b, v204
	v_bitop3_b32 v36, s46, v145, v140 bitop3:0xde
	v_mul_lo_u32 v36, v36, s33
	v_add_u32_e32 v206, v105, v36
	ds_read_b128 v[212:215], v206
	ds_read_b128 v[216:219], v206 offset:64
	ds_read_b128 v[220:223], v206 offset:128
	ds_read_b128 v[224:227], v206 offset:192
	ds_read_b128 v[228:231], v206 offset:4352
	ds_read_b128 v[232:235], v206 offset:4416
	ds_read_b128 v[236:239], v206 offset:4480
	ds_read_b128 v[244:247], v206 offset:4544
	ds_read_b128 v[248:251], v206 offset:8704
	ds_read_b128 v[252:255], v206 offset:8768
	s_mov_b32 s30, s28
	s_mov_b32 s31, s28
	s_mov_b32 s29, s28
	v_mov_b64_e32 v[38:39], s[30:31]
	s_and_b64 vcc, exec, s[8:9]
	v_mov_b64_e32 v[36:37], s[28:29]
	s_waitcnt lgkmcnt(9)
	v_mfma_f32_16x16x32_bf16 v[44:47], v[212:215], v[32:35], 0
	v_mfma_f32_16x16x32_bf16 v[48:51], v[212:215], v[20:23], 0
	s_cbranch_vccnz .LBB0_867
	v_mfma_f32_16x16x32_bf16 v[36:39], v[212:215], v[0:3], 0
